# K-loop LDS-DMA issue: SGPR base + 32-bit lane offset addressing, second piece m0 via s_add (no v_readfirstlane / 64-bit VALU add per DMA)
# speedup vs baseline: 1.0099x; 1.0019x over previous
.LBB0_63:
	ds_read_b128 v[150:153], v149 offset:0
	ds_read_b128 v[158:161], v149 offset:1024
	ds_read_b128 v[162:165], v149 offset:2048
	ds_read_b128 v[166:169], v149 offset:3072
	s_add_u32 s37, s7, s14
	s_addc_u32 s39, s20, s15
	s_add_u32 s38, s37, 0x80
	v_add_u32_e32 v156, 0xc000, v135
	s_addc_u32 s39, s39, 0
	v_readfirstlane_b32 s37, v156
	v_add_u32_e32 v157, 0xe000, v135
	s_mov_b32 m0, s37
	ds_read_b128 v[170:173], v148 offset:0
	ds_read_b128 v[178:181], v148 offset:1024
	ds_read_b128 v[182:185], v148 offset:2048
	ds_read_b128 v[186:189], v148 offset:3072
	ds_read_b128 v[190:193], v148 offset:4096
	ds_read_b128 v[194:197], v148 offset:5120
	ds_read_b128 v[198:201], v148 offset:6144
	ds_read_b128 v[202:205], v148 offset:7168
	global_load_lds_dwordx4 v130, s[38:39]
	s_add_u32 m0, m0, 0x2000
	s_nop 0
	global_load_lds_dwordx4 v128, s[38:39]
	ds_read_b128 v[206:209], v147 offset:0
	ds_read_b128 v[210:213], v147 offset:1024
	ds_read_b128 v[214:217], v147 offset:2048
	ds_read_b128 v[218:221], v147 offset:3072
	s_waitcnt vmcnt(8)
	s_waitcnt lgkmcnt(0)
	s_barrier
	s_waitcnt lgkmcnt(0)
	s_waitcnt lgkmcnt(0)
	s_setprio 1
	v_mfma_f32_16x16x32_bf16 v[124:127], v[150:153], v[170:173], v[124:127]
	v_mfma_f32_16x16x32_bf16 v[120:123], v[162:165], v[170:173], v[120:123]
	v_mfma_f32_16x16x32_bf16 v[116:119], v[150:153], v[182:185], v[116:119]
	v_mfma_f32_16x16x32_bf16 v[112:115], v[162:165], v[182:185], v[112:115]
	v_mfma_f32_16x16x32_bf16 v[108:111], v[150:153], v[190:193], v[108:111]
	v_mfma_f32_16x16x32_bf16 v[104:107], v[162:165], v[190:193], v[104:107]
	v_mfma_f32_16x16x32_bf16 v[100:103], v[150:153], v[198:201], v[100:103]
	v_mfma_f32_16x16x32_bf16 v[96:99], v[162:165], v[198:201], v[96:99]
	v_mfma_f32_16x16x32_bf16 v[124:127], v[158:161], v[178:181], v[124:127]
	v_mfma_f32_16x16x32_bf16 v[120:123], v[166:169], v[178:181], v[120:123]
	v_mfma_f32_16x16x32_bf16 v[116:119], v[158:161], v[186:189], v[116:119]
	v_mfma_f32_16x16x32_bf16 v[112:115], v[166:169], v[186:189], v[112:115]
	v_mfma_f32_16x16x32_bf16 v[108:111], v[158:161], v[194:197], v[108:111]
	v_mfma_f32_16x16x32_bf16 v[104:107], v[166:169], v[194:197], v[104:107]
	v_mfma_f32_16x16x32_bf16 v[100:103], v[158:161], v[202:205], v[100:103]
	v_mfma_f32_16x16x32_bf16 v[96:99], v[166:169], v[202:205], v[96:99]
	s_setprio 0
	s_waitcnt lgkmcnt(0)
	s_setprio 1
	v_mfma_f32_16x16x32_bf16 v[92:95], v[206:209], v[170:173], v[92:95]
	v_mfma_f32_16x16x32_bf16 v[88:91], v[214:217], v[170:173], v[88:91]
	v_mfma_f32_16x16x32_bf16 v[84:87], v[206:209], v[182:185], v[84:87]
	v_mfma_f32_16x16x32_bf16 v[80:83], v[214:217], v[182:185], v[80:83]
	v_mfma_f32_16x16x32_bf16 v[76:79], v[206:209], v[190:193], v[76:79]
	v_mfma_f32_16x16x32_bf16 v[72:75], v[214:217], v[190:193], v[72:75]
	v_mfma_f32_16x16x32_bf16 v[68:71], v[206:209], v[198:201], v[68:71]
	v_mfma_f32_16x16x32_bf16 v[64:67], v[214:217], v[198:201], v[64:67]
	v_mfma_f32_16x16x32_bf16 v[92:95], v[210:213], v[178:181], v[92:95]
	v_mfma_f32_16x16x32_bf16 v[88:91], v[218:221], v[178:181], v[88:91]
	v_mfma_f32_16x16x32_bf16 v[84:87], v[210:213], v[186:189], v[84:87]
	v_mfma_f32_16x16x32_bf16 v[80:83], v[218:221], v[186:189], v[80:83]
	v_mfma_f32_16x16x32_bf16 v[76:79], v[210:213], v[194:197], v[76:79]
	v_mfma_f32_16x16x32_bf16 v[72:75], v[218:221], v[194:197], v[72:75]
	v_mfma_f32_16x16x32_bf16 v[68:71], v[210:213], v[202:205], v[68:71]
	v_mfma_f32_16x16x32_bf16 v[64:67], v[218:221], v[202:205], v[64:67]
	s_setprio 0
	s_barrier
	s_add_u32 s37, s21, s14
	s_addc_u32 s40, s26, s15
	s_add_u32 s38, s37, 0x100
	s_addc_u32 s39, s40, 0
	v_readfirstlane_b32 s41, v141
	s_mov_b32 m0, s41
	s_nop 0
	global_load_lds_dwordx4 v176, s[38:39]
	s_add_u32 m0, m0, 0x2000
	s_nop 0
	global_load_lds_dwordx4 v132, s[38:39]
	s_add_u32 s41, s2, s14
	s_addc_u32 s42, s3, s15
	s_add_u32 s38, s41, 0x100
	s_addc_u32 s39, s42, 0
	v_readfirstlane_b32 s43, v135
	s_mov_b32 m0, s43
	ds_read_b128 v[170:173], v146 offset:0
	ds_read_b128 v[178:181], v146 offset:1024
	ds_read_b128 v[182:185], v146 offset:2048
	ds_read_b128 v[186:189], v146 offset:3072
	ds_read_b128 v[190:193], v146 offset:4096
	ds_read_b128 v[194:197], v146 offset:5120
	ds_read_b128 v[198:201], v146 offset:6144
	ds_read_b128 v[202:205], v146 offset:7168
	global_load_lds_dwordx4 v130, s[38:39]
	s_add_u32 m0, m0, 0x2000
	s_nop 0
	global_load_lds_dwordx4 v128, s[38:39]
	s_add_u32 s43, s18, s14
	s_addc_u32 s44, s19, s15
	s_add_u32 s38, s43, 0x100
	s_addc_u32 s39, s44, 0
	v_readfirstlane_b32 s45, v139
	s_mov_b32 m0, s45
	s_nop 0
	global_load_lds_dwordx4 v176, s[38:39]
	s_add_u32 m0, m0, 0x2000
	s_nop 0
	global_load_lds_dwordx4 v132, s[38:39]
	s_waitcnt vmcnt(8)
	s_waitcnt lgkmcnt(0)
	s_barrier
	s_waitcnt lgkmcnt(0)
	s_setprio 1
	v_mfma_f32_16x16x32_bf16 v[60:63], v[150:153], v[170:173], v[60:63]
	v_mfma_f32_16x16x32_bf16 v[56:59], v[162:165], v[170:173], v[56:59]
	v_mfma_f32_16x16x32_bf16 v[52:55], v[150:153], v[182:185], v[52:55]
	v_mfma_f32_16x16x32_bf16 v[48:51], v[162:165], v[182:185], v[48:51]
	v_mfma_f32_16x16x32_bf16 v[44:47], v[150:153], v[190:193], v[44:47]
	v_mfma_f32_16x16x32_bf16 v[40:43], v[162:165], v[190:193], v[40:43]
	v_mfma_f32_16x16x32_bf16 v[36:39], v[150:153], v[198:201], v[36:39]
	v_mfma_f32_16x16x32_bf16 v[32:35], v[162:165], v[198:201], v[32:35]
	v_mfma_f32_16x16x32_bf16 v[60:63], v[158:161], v[178:181], v[60:63]
	v_mfma_f32_16x16x32_bf16 v[56:59], v[166:169], v[178:181], v[56:59]
	v_mfma_f32_16x16x32_bf16 v[52:55], v[158:161], v[186:189], v[52:55]
	v_mfma_f32_16x16x32_bf16 v[48:51], v[166:169], v[186:189], v[48:51]
	v_mfma_f32_16x16x32_bf16 v[44:47], v[158:161], v[194:197], v[44:47]
	v_mfma_f32_16x16x32_bf16 v[40:43], v[166:169], v[194:197], v[40:43]
	v_mfma_f32_16x16x32_bf16 v[36:39], v[158:161], v[202:205], v[36:39]
	v_mfma_f32_16x16x32_bf16 v[32:35], v[166:169], v[202:205], v[32:35]
	s_setprio 0
	s_setprio 1
	v_mfma_f32_16x16x32_bf16 v[28:31], v[206:209], v[170:173], v[28:31]
	v_mfma_f32_16x16x32_bf16 v[24:27], v[214:217], v[170:173], v[24:27]
	v_mfma_f32_16x16x32_bf16 v[20:23], v[206:209], v[182:185], v[20:23]
	v_mfma_f32_16x16x32_bf16 v[16:19], v[214:217], v[182:185], v[16:19]
	v_mfma_f32_16x16x32_bf16 v[12:15], v[206:209], v[190:193], v[12:15]
	v_mfma_f32_16x16x32_bf16 v[8:11], v[214:217], v[190:193], v[8:11]
	v_mfma_f32_16x16x32_bf16 v[4:7], v[206:209], v[198:201], v[4:7]
	v_mfma_f32_16x16x32_bf16 v[0:3], v[214:217], v[198:201], v[0:3]
	v_mfma_f32_16x16x32_bf16 v[28:31], v[210:213], v[178:181], v[28:31]
	v_mfma_f32_16x16x32_bf16 v[24:27], v[218:221], v[178:181], v[24:27]
	v_mfma_f32_16x16x32_bf16 v[20:23], v[210:213], v[186:189], v[20:23]
	v_mfma_f32_16x16x32_bf16 v[16:19], v[218:221], v[186:189], v[16:19]
	v_mfma_f32_16x16x32_bf16 v[12:15], v[210:213], v[194:197], v[12:15]
	v_mfma_f32_16x16x32_bf16 v[8:11], v[218:221], v[194:197], v[8:11]
	v_mfma_f32_16x16x32_bf16 v[4:7], v[210:213], v[202:205], v[4:7]
	v_mfma_f32_16x16x32_bf16 v[0:3], v[218:221], v[202:205], v[0:3]
	s_setprio 0
	s_barrier
	ds_read_b128 v[158:161], v145 offset:0
	ds_read_b128 v[162:165], v145 offset:1024
	ds_read_b128 v[166:169], v145 offset:2048
	ds_read_b128 v[170:173], v145 offset:3072
	s_add_u32 s38, s27, s14
	s_addc_u32 s39, s28, s15
	v_readfirstlane_b32 s45, v137
	s_mov_b32 m0, s45
	ds_read_b128 v[152:155], v144 offset:0
	ds_read_b128 v[178:181], v144 offset:1024
	ds_read_b128 v[182:185], v144 offset:2048
	ds_read_b128 v[186:189], v144 offset:3072
	ds_read_b128 v[190:193], v144 offset:4096
	ds_read_b128 v[194:197], v144 offset:5120
	ds_read_b128 v[198:201], v144 offset:6144
	ds_read_b128 v[202:205], v144 offset:7168
	s_nop 0
	global_load_lds_dwordx4 v130, s[38:39]
	s_add_u32 m0, m0, 0x2000
	s_nop 0
	global_load_lds_dwordx4 v128, s[38:39]
	ds_read_b128 v[206:209], v143 offset:0
	ds_read_b128 v[210:213], v143 offset:1024
	ds_read_b128 v[214:217], v143 offset:2048
	ds_read_b128 v[218:221], v143 offset:3072
	s_waitcnt vmcnt(8)
	s_waitcnt lgkmcnt(0)
	s_barrier
	s_waitcnt lgkmcnt(0)
	s_waitcnt lgkmcnt(0)
	s_setprio 1
	v_mfma_f32_16x16x32_bf16 v[124:127], v[158:161], v[152:155], v[124:127]
	v_mfma_f32_16x16x32_bf16 v[120:123], v[166:169], v[152:155], v[120:123]
	v_mfma_f32_16x16x32_bf16 v[116:119], v[158:161], v[182:185], v[116:119]
	v_mfma_f32_16x16x32_bf16 v[112:115], v[166:169], v[182:185], v[112:115]
	v_mfma_f32_16x16x32_bf16 v[108:111], v[158:161], v[190:193], v[108:111]
	v_mfma_f32_16x16x32_bf16 v[104:107], v[166:169], v[190:193], v[104:107]
	v_mfma_f32_16x16x32_bf16 v[100:103], v[158:161], v[198:201], v[100:103]
	v_mfma_f32_16x16x32_bf16 v[96:99], v[166:169], v[198:201], v[96:99]
	v_mfma_f32_16x16x32_bf16 v[124:127], v[162:165], v[178:181], v[124:127]
	v_mfma_f32_16x16x32_bf16 v[120:123], v[170:173], v[178:181], v[120:123]
	v_mfma_f32_16x16x32_bf16 v[116:119], v[162:165], v[186:189], v[116:119]
	v_mfma_f32_16x16x32_bf16 v[112:115], v[170:173], v[186:189], v[112:115]
	v_mfma_f32_16x16x32_bf16 v[108:111], v[162:165], v[194:197], v[108:111]
	v_mfma_f32_16x16x32_bf16 v[104:107], v[170:173], v[194:197], v[104:107]
	v_mfma_f32_16x16x32_bf16 v[100:103], v[162:165], v[202:205], v[100:103]
	v_mfma_f32_16x16x32_bf16 v[96:99], v[170:173], v[202:205], v[96:99]
	s_setprio 0
	s_waitcnt lgkmcnt(0)
	s_setprio 1
	v_mfma_f32_16x16x32_bf16 v[92:95], v[206:209], v[152:155], v[92:95]
	v_mfma_f32_16x16x32_bf16 v[88:91], v[214:217], v[152:155], v[88:91]
	v_mfma_f32_16x16x32_bf16 v[84:87], v[206:209], v[182:185], v[84:87]
	v_mfma_f32_16x16x32_bf16 v[80:83], v[214:217], v[182:185], v[80:83]
	v_mfma_f32_16x16x32_bf16 v[76:79], v[206:209], v[190:193], v[76:79]
	v_mfma_f32_16x16x32_bf16 v[72:75], v[214:217], v[190:193], v[72:75]
	v_mfma_f32_16x16x32_bf16 v[68:71], v[206:209], v[198:201], v[68:71]
	v_mfma_f32_16x16x32_bf16 v[64:67], v[214:217], v[198:201], v[64:67]
	v_mfma_f32_16x16x32_bf16 v[92:95], v[210:213], v[178:181], v[92:95]
	v_mfma_f32_16x16x32_bf16 v[88:91], v[218:221], v[178:181], v[88:91]
	v_mfma_f32_16x16x32_bf16 v[84:87], v[210:213], v[186:189], v[84:87]
	v_mfma_f32_16x16x32_bf16 v[80:83], v[218:221], v[186:189], v[80:83]
	v_mfma_f32_16x16x32_bf16 v[76:79], v[210:213], v[194:197], v[76:79]
	v_mfma_f32_16x16x32_bf16 v[72:75], v[218:221], v[194:197], v[72:75]
	v_mfma_f32_16x16x32_bf16 v[68:71], v[210:213], v[202:205], v[68:71]
	v_mfma_f32_16x16x32_bf16 v[64:67], v[218:221], v[202:205], v[64:67]
	s_setprio 0
	s_barrier
	s_add_u32 s38, s37, 0x180
	v_add_u32_e32 v150, 0x18000, v135
	s_addc_u32 s39, s40, 0
	v_readfirstlane_b32 s37, v150
	v_add_u32_e32 v151, 0x1a000, v135
	s_mov_b32 m0, s37
	global_load_lds_dwordx4 v176, s[38:39]
	s_add_u32 m0, m0, 0x2000
	s_nop 0
	global_load_lds_dwordx4 v132, s[38:39]
	s_add_u32 s38, s41, 0x180
	v_add_u32_e32 v152, 0x8000, v135
	s_addc_u32 s39, s42, 0
	v_readfirstlane_b32 s37, v152
	v_add_u32_e32 v153, 0xa000, v135
	s_mov_b32 m0, s37
	ds_read_b128 v[178:181], v142 offset:0
	ds_read_b128 v[182:185], v142 offset:1024
	ds_read_b128 v[186:189], v142 offset:2048
	ds_read_b128 v[190:193], v142 offset:3072
	ds_read_b128 v[194:197], v142 offset:4096
	ds_read_b128 v[198:201], v142 offset:5120
	ds_read_b128 v[202:205], v142 offset:6144
	ds_read_b128 v[222:225], v142 offset:7168
	global_load_lds_dwordx4 v130, s[38:39]
	s_add_u32 m0, m0, 0x2000
	s_nop 0
	global_load_lds_dwordx4 v128, s[38:39]
	s_add_u32 s38, s43, 0x180
	v_add_u32_e32 v154, 0x1c000, v135
	s_addc_u32 s39, s44, 0
	v_readfirstlane_b32 s37, v154
	v_add_u32_e32 v155, 0x1e000, v135
	s_mov_b32 m0, s37
	global_load_lds_dwordx4 v176, s[38:39]
	s_add_u32 m0, m0, 0x2000
	s_nop 0
	global_load_lds_dwordx4 v132, s[38:39]
	s_waitcnt vmcnt(8)
	s_waitcnt lgkmcnt(0)
	s_barrier
	s_waitcnt lgkmcnt(0)
	s_setprio 1
	v_mfma_f32_16x16x32_bf16 v[60:63], v[158:161], v[178:181], v[60:63]
	v_mfma_f32_16x16x32_bf16 v[56:59], v[166:169], v[178:181], v[56:59]
	v_mfma_f32_16x16x32_bf16 v[52:55], v[158:161], v[186:189], v[52:55]
	v_mfma_f32_16x16x32_bf16 v[48:51], v[166:169], v[186:189], v[48:51]
	v_mfma_f32_16x16x32_bf16 v[44:47], v[158:161], v[194:197], v[44:47]
	v_mfma_f32_16x16x32_bf16 v[40:43], v[166:169], v[194:197], v[40:43]
	v_mfma_f32_16x16x32_bf16 v[36:39], v[158:161], v[202:205], v[36:39]
	v_mfma_f32_16x16x32_bf16 v[32:35], v[166:169], v[202:205], v[32:35]
	v_mfma_f32_16x16x32_bf16 v[60:63], v[162:165], v[182:185], v[60:63]
	v_mfma_f32_16x16x32_bf16 v[56:59], v[170:173], v[182:185], v[56:59]
	v_mfma_f32_16x16x32_bf16 v[52:55], v[162:165], v[190:193], v[52:55]
	v_mfma_f32_16x16x32_bf16 v[48:51], v[170:173], v[190:193], v[48:51]
	v_mfma_f32_16x16x32_bf16 v[44:47], v[162:165], v[198:201], v[44:47]
	v_mfma_f32_16x16x32_bf16 v[40:43], v[170:173], v[198:201], v[40:43]
	v_mfma_f32_16x16x32_bf16 v[36:39], v[162:165], v[222:225], v[36:39]
	v_mfma_f32_16x16x32_bf16 v[32:35], v[170:173], v[222:225], v[32:35]
	s_setprio 0
	s_setprio 1
	v_mfma_f32_16x16x32_bf16 v[28:31], v[206:209], v[178:181], v[28:31]
	v_mfma_f32_16x16x32_bf16 v[24:27], v[214:217], v[178:181], v[24:27]
	v_mfma_f32_16x16x32_bf16 v[20:23], v[206:209], v[186:189], v[20:23]
	v_mfma_f32_16x16x32_bf16 v[16:19], v[214:217], v[186:189], v[16:19]
	v_mfma_f32_16x16x32_bf16 v[12:15], v[206:209], v[194:197], v[12:15]
	v_mfma_f32_16x16x32_bf16 v[8:11], v[214:217], v[194:197], v[8:11]
	v_mfma_f32_16x16x32_bf16 v[4:7], v[206:209], v[202:205], v[4:7]
	v_mfma_f32_16x16x32_bf16 v[0:3], v[214:217], v[202:205], v[0:3]
	v_mfma_f32_16x16x32_bf16 v[28:31], v[210:213], v[182:185], v[28:31]
	v_mfma_f32_16x16x32_bf16 v[24:27], v[218:221], v[182:185], v[24:27]
	v_mfma_f32_16x16x32_bf16 v[20:23], v[210:213], v[190:193], v[20:23]
	v_mfma_f32_16x16x32_bf16 v[16:19], v[218:221], v[190:193], v[16:19]
	v_mfma_f32_16x16x32_bf16 v[12:15], v[210:213], v[198:201], v[12:15]
	v_mfma_f32_16x16x32_bf16 v[8:11], v[218:221], v[198:201], v[8:11]
	v_mfma_f32_16x16x32_bf16 v[4:7], v[210:213], v[222:225], v[4:7]
	v_mfma_f32_16x16x32_bf16 v[0:3], v[218:221], v[222:225], v[0:3]
	s_setprio 0
	s_add_i32 s29, s29, 2
	s_add_u32 s14, s14, 0x100
	s_addc_u32 s15, s15, 0
	s_cmp_gt_u32 s29, 11
	s_barrier
	s_cbranch_scc0 .LBB0_63
	v_add_u32_e32 v156, 0xc000, v135
	v_add_u32_e32 v157, 0xe000, v135
	v_add_u32_e32 v150, 0x18000, v135
	v_add_u32_e32 v151, 0x1a000, v135
	v_add_u32_e32 v152, 0x8000, v135
	v_add_u32_e32 v153, 0xa000, v135
	v_add_u32_e32 v154, 0x1c000, v135
	v_add_u32_e32 v155, 0x1e000, v135
	s_add_u32 s2, s7, 0x780
	s_addc_u32 s3, s20, 0
	v_readfirstlane_b32 s7, v156
	ds_read_b128 v[158:161], v149 offset:0
	ds_read_b128 v[162:165], v149 offset:1024
	ds_read_b128 v[166:169], v149 offset:2048
	ds_read_b128 v[170:173], v149 offset:3072
	ds_read_b128 v[178:181], v148 offset:0
	ds_read_b128 v[182:185], v148 offset:1024
	ds_read_b128 v[186:189], v148 offset:2048
	ds_read_b128 v[190:193], v148 offset:3072
	ds_read_b128 v[194:197], v148 offset:4096
	ds_read_b128 v[198:201], v148 offset:5120
	ds_read_b128 v[202:205], v148 offset:6144
	ds_read_b128 v[206:209], v148 offset:7168
	v_lshl_add_u64 v[148:149], s[2:3], 0, v[130:131]
	s_mov_b32 m0, s7
	s_nop 0
	global_load_lds_dwordx4 v[148:149], off
	v_lshl_add_u64 v[148:149], s[2:3], 0, v[128:129]
	v_readfirstlane_b32 s2, v157
	s_mov_b32 m0, s2
	s_nop 0
	global_load_lds_dwordx4 v[148:149], off
	s_waitcnt vmcnt(10)
	s_barrier
	s_waitcnt lgkmcnt(0)
	s_waitcnt lgkmcnt(0)
	s_setprio 1
	v_mfma_f32_16x16x32_bf16 v[124:127], v[158:161], v[178:181], v[124:127]
	v_mfma_f32_16x16x32_bf16 v[120:123], v[166:169], v[178:181], v[120:123]
	v_mfma_f32_16x16x32_bf16 v[116:119], v[158:161], v[186:189], v[116:119]
	v_mfma_f32_16x16x32_bf16 v[112:115], v[166:169], v[186:189], v[112:115]
	v_mfma_f32_16x16x32_bf16 v[100:103], v[158:161], v[202:205], v[100:103]
	v_mfma_f32_16x16x32_bf16 v[96:99], v[166:169], v[202:205], v[96:99]
	v_mfma_f32_16x16x32_bf16 v[124:127], v[162:165], v[182:185], v[124:127]
	v_mfma_f32_16x16x32_bf16 v[120:123], v[170:173], v[182:185], v[120:123]
	v_mfma_f32_16x16x32_bf16 v[116:119], v[162:165], v[190:193], v[116:119]
	v_mfma_f32_16x16x32_bf16 v[112:115], v[170:173], v[190:193], v[112:115]
	v_mfma_f32_16x16x32_bf16 v[108:111], v[158:161], v[194:197], v[108:111]
	v_mfma_f32_16x16x32_bf16 v[104:107], v[166:169], v[194:197], v[104:107]
	v_mfma_f32_16x16x32_bf16 v[100:103], v[162:165], v[206:209], v[100:103]
	v_mfma_f32_16x16x32_bf16 v[96:99], v[170:173], v[206:209], v[96:99]
	v_mfma_f32_16x16x32_bf16 v[210:213], v[162:165], v[198:201], v[108:111]
	v_mfma_f32_16x16x32_bf16 v[214:217], v[170:173], v[198:201], v[104:107]
	s_setprio 0
	s_barrier
	ds_read_b128 v[104:107], v147 offset:0
	ds_read_b128 v[108:111], v147 offset:1024
	ds_read_b128 v[218:221], v147 offset:2048
	ds_read_b128 v[222:225], v147 offset:3072
	s_waitcnt vmcnt(8)
	s_barrier
	s_waitcnt lgkmcnt(0)
	s_setprio 1
	v_mfma_f32_16x16x32_bf16 v[92:95], v[104:107], v[178:181], v[92:95]
	v_mfma_f32_16x16x32_bf16 v[88:91], v[218:221], v[178:181], v[88:91]
	v_mfma_f32_16x16x32_bf16 v[76:79], v[104:107], v[194:197], v[76:79]
	v_mfma_f32_16x16x32_bf16 v[72:75], v[218:221], v[194:197], v[72:75]
	v_mfma_f32_16x16x32_bf16 v[68:71], v[104:107], v[202:205], v[68:71]
	v_mfma_f32_16x16x32_bf16 v[92:95], v[108:111], v[182:185], v[92:95]
	v_mfma_f32_16x16x32_bf16 v[88:91], v[222:225], v[182:185], v[88:91]
	v_mfma_f32_16x16x32_bf16 v[84:87], v[104:107], v[186:189], v[84:87]
	v_mfma_f32_16x16x32_bf16 v[80:83], v[218:221], v[186:189], v[80:83]
	v_mfma_f32_16x16x32_bf16 v[76:79], v[108:111], v[198:201], v[76:79]
	v_mfma_f32_16x16x32_bf16 v[72:75], v[222:225], v[198:201], v[72:75]
	v_mfma_f32_16x16x32_bf16 v[68:71], v[108:111], v[206:209], v[68:71]
	v_mfma_f32_16x16x32_bf16 v[64:67], v[218:221], v[202:205], v[64:67]
	v_mfma_f32_16x16x32_bf16 v[178:181], v[108:111], v[190:193], v[84:87]
	v_mfma_f32_16x16x32_bf16 v[182:185], v[222:225], v[190:193], v[80:83]
	v_mfma_f32_16x16x32_bf16 v[186:189], v[222:225], v[206:209], v[64:67]
	s_setprio 0
	s_barrier
	ds_read_b128 v[64:67], v146 offset:0
	ds_read_b128 v[80:83], v146 offset:1024
	ds_read_b128 v[84:87], v146 offset:2048
	ds_read_b128 v[190:193], v146 offset:3072
	ds_read_b128 v[194:197], v146 offset:4096
	ds_read_b128 v[198:201], v146 offset:5120
	ds_read_b128 v[202:205], v146 offset:6144
	ds_read_b128 v[146:149], v146 offset:7168
	s_waitcnt vmcnt(4)
	s_barrier
	s_waitcnt lgkmcnt(0)
	s_setprio 1
	s_nop 0
	v_mfma_f32_16x16x32_bf16 v[60:63], v[158:161], v[64:67], v[60:63]
	v_mfma_f32_16x16x32_bf16 v[56:59], v[166:169], v[64:67], v[56:59]
	v_mfma_f32_16x16x32_bf16 v[60:63], v[162:165], v[80:83], v[60:63]
	v_mfma_f32_16x16x32_bf16 v[56:59], v[170:173], v[80:83], v[56:59]
	v_mfma_f32_16x16x32_bf16 v[52:55], v[158:161], v[84:87], v[52:55]
	v_mfma_f32_16x16x32_bf16 v[48:51], v[166:169], v[84:87], v[48:51]
	v_mfma_f32_16x16x32_bf16 v[44:47], v[158:161], v[194:197], v[44:47]
	v_mfma_f32_16x16x32_bf16 v[40:43], v[166:169], v[194:197], v[40:43]
	v_mfma_f32_16x16x32_bf16 v[36:39], v[158:161], v[202:205], v[36:39]
	v_mfma_f32_16x16x32_bf16 v[32:35], v[166:169], v[202:205], v[32:35]
	v_mfma_f32_16x16x32_bf16 v[206:209], v[162:165], v[190:193], v[52:55]
	v_mfma_f32_16x16x32_bf16 v[226:229], v[170:173], v[190:193], v[48:51]
	v_mfma_f32_16x16x32_bf16 v[232:235], v[162:165], v[198:201], v[44:47]
	v_mfma_f32_16x16x32_bf16 v[238:241], v[170:173], v[198:201], v[40:43]
	v_mfma_f32_16x16x32_bf16 v[156:159], v[162:165], v[146:149], v[36:39]
	v_mfma_f32_16x16x32_bf16 v[160:163], v[170:173], v[146:149], v[32:35]
	s_setprio 0
	s_setprio 1
	v_mfma_f32_16x16x32_bf16 v[28:31], v[104:107], v[64:67], v[28:31]
	v_mfma_f32_16x16x32_bf16 v[24:27], v[218:221], v[64:67], v[24:27]
	v_mfma_f32_16x16x32_bf16 v[12:15], v[104:107], v[194:197], v[12:15]
	v_mfma_f32_16x16x32_bf16 v[8:11], v[218:221], v[194:197], v[8:11]
	v_mfma_f32_16x16x32_bf16 v[28:31], v[108:111], v[80:83], v[28:31]
	v_mfma_f32_16x16x32_bf16 v[24:27], v[222:225], v[80:83], v[24:27]
	v_mfma_f32_16x16x32_bf16 v[20:23], v[104:107], v[84:87], v[20:23]
	v_mfma_f32_16x16x32_bf16 v[16:19], v[218:221], v[84:87], v[16:19]
	v_mfma_f32_16x16x32_bf16 v[12:15], v[108:111], v[198:201], v[12:15]
	v_mfma_f32_16x16x32_bf16 v[8:11], v[222:225], v[198:201], v[8:11]
	v_mfma_f32_16x16x32_bf16 v[4:7], v[104:107], v[202:205], v[4:7]
	v_mfma_f32_16x16x32_bf16 v[0:3], v[218:221], v[202:205], v[0:3]
	v_mfma_f32_16x16x32_bf16 v[164:167], v[108:111], v[190:193], v[20:23]
	v_mfma_f32_16x16x32_bf16 v[168:171], v[222:225], v[190:193], v[16:19]
	v_mfma_f32_16x16x32_bf16 v[172:175], v[108:111], v[146:149], v[4:7]
	v_mfma_f32_16x16x32_bf16 v[146:149], v[222:225], v[146:149], v[0:3]
	s_setprio 0
	s_barrier
	ds_read_b128 v[0:3], v145 offset:0
	ds_read_b128 v[4:7], v145 offset:1024
	ds_read_b128 v[190:193], v145 offset:2048
	ds_read_b128 v[194:197], v145 offset:3072
	ds_read_b128 v[16:19], v144 offset:0
	ds_read_b128 v[20:23], v144 offset:1024
	ds_read_b128 v[40:43], v144 offset:2048
	ds_read_b128 v[44:47], v144 offset:3072
	ds_read_b128 v[64:67], v144 offset:4096
	ds_read_b128 v[198:201], v144 offset:5120
	ds_read_b128 v[202:205], v144 offset:6144
	ds_read_b128 v[218:221], v144 offset:7168
	s_waitcnt vmcnt(2)
	s_barrier
	s_waitcnt lgkmcnt(0)
	s_waitcnt lgkmcnt(0)
	s_setprio 1
	v_mfma_f32_16x16x32_bf16 v[32:35], v[0:3], v[16:19], v[124:127]
	v_mfma_f32_16x16x32_bf16 v[104:107], v[4:7], v[20:23], v[32:35]
	v_mfma_f32_16x16x32_bf16 v[32:35], v[190:193], v[16:19], v[120:123]
	v_mfma_f32_16x16x32_bf16 v[108:111], v[194:197], v[20:23], v[32:35]
	v_mfma_f32_16x16x32_bf16 v[32:35], v[0:3], v[40:43], v[116:119]
	v_mfma_f32_16x16x32_bf16 v[80:83], v[4:7], v[44:47], v[32:35]
	v_mfma_f32_16x16x32_bf16 v[32:35], v[190:193], v[40:43], v[112:115]
	v_mfma_f32_16x16x32_bf16 v[84:87], v[194:197], v[44:47], v[32:35]
	v_mfma_f32_16x16x32_bf16 v[32:35], v[0:3], v[64:67], v[210:213]
	v_mfma_f32_16x16x32_bf16 v[48:51], v[4:7], v[198:201], v[32:35]
	v_mfma_f32_16x16x32_bf16 v[32:35], v[190:193], v[64:67], v[214:217]
	v_mfma_f32_16x16x32_bf16 v[52:55], v[194:197], v[198:201], v[32:35]
	v_mfma_f32_16x16x32_bf16 v[32:35], v[0:3], v[202:205], v[100:103]
	v_mfma_f32_16x16x32_bf16 v[36:39], v[190:193], v[202:205], v[96:99]
	v_mfma_f32_16x16x32_bf16 v[32:35], v[4:7], v[218:221], v[32:35]
	v_mfma_f32_16x16x32_bf16 v[36:39], v[194:197], v[218:221], v[36:39]
	s_setprio 0
	s_barrier
	ds_read_b128 v[210:213], v143 offset:0
	ds_read_b128 v[214:217], v143 offset:1024
	ds_read_b128 v[222:225], v143 offset:2048
	ds_read_b128 v[242:245], v143 offset:3072
	s_waitcnt vmcnt(0)
	s_barrier
	s_waitcnt lgkmcnt(0)
	s_setprio 1
	v_mfma_f32_16x16x32_bf16 v[92:95], v[210:213], v[16:19], v[92:95]
	v_mfma_f32_16x16x32_bf16 v[16:19], v[222:225], v[16:19], v[88:91]
	v_mfma_f32_16x16x32_bf16 v[124:127], v[242:245], v[20:23], v[16:19]
	v_mfma_f32_16x16x32_bf16 v[16:19], v[210:213], v[40:43], v[178:181]
	v_mfma_f32_16x16x32_bf16 v[112:115], v[214:217], v[44:47], v[16:19]
	v_mfma_f32_16x16x32_bf16 v[16:19], v[222:225], v[40:43], v[182:185]
	v_mfma_f32_16x16x32_bf16 v[116:119], v[242:245], v[44:47], v[16:19]
	v_mfma_f32_16x16x32_bf16 v[16:19], v[210:213], v[64:67], v[76:79]
	v_mfma_f32_16x16x32_bf16 v[96:99], v[214:217], v[198:201], v[16:19]
	v_mfma_f32_16x16x32_bf16 v[16:19], v[222:225], v[64:67], v[72:75]
	v_mfma_f32_16x16x32_bf16 v[100:103], v[242:245], v[198:201], v[16:19]
	v_mfma_f32_16x16x32_bf16 v[16:19], v[210:213], v[202:205], v[68:71]
	v_mfma_f32_16x16x32_bf16 v[64:67], v[214:217], v[218:221], v[16:19]
	v_mfma_f32_16x16x32_bf16 v[16:19], v[222:225], v[202:205], v[186:189]
	v_mfma_f32_16x16x32_bf16 v[120:123], v[214:217], v[20:23], v[92:95]
	v_mfma_f32_16x16x32_bf16 v[68:71], v[242:245], v[218:221], v[16:19]
	s_setprio 0
	s_barrier
	ds_read_b128 v[92:95], v142 offset:0
	ds_read_b128 v[178:181], v142 offset:1024
	ds_read_b128 v[182:185], v142 offset:2048
	ds_read_b128 v[186:189], v142 offset:3072
	ds_read_b128 v[198:201], v142 offset:4096
	ds_read_b128 v[202:205], v142 offset:5120
	ds_read_b128 v[218:221], v142 offset:6144
	ds_read_b128 v[142:145], v142 offset:7168
	s_barrier
	s_waitcnt lgkmcnt(0)
	s_setprio 1
	v_mfma_f32_16x16x32_bf16 v[16:19], v[0:3], v[92:95], v[60:63]
	v_mfma_f32_16x16x32_bf16 v[72:75], v[4:7], v[178:181], v[16:19]
	v_mfma_f32_16x16x32_bf16 v[16:19], v[190:193], v[92:95], v[56:59]
	v_mfma_f32_16x16x32_bf16 v[76:79], v[194:197], v[178:181], v[16:19]
	v_mfma_f32_16x16x32_bf16 v[16:19], v[0:3], v[182:185], v[206:209]
	v_mfma_f32_16x16x32_bf16 v[40:43], v[4:7], v[186:189], v[16:19]
	v_mfma_f32_16x16x32_bf16 v[16:19], v[190:193], v[182:185], v[226:229]
	v_mfma_f32_16x16x32_bf16 v[44:47], v[194:197], v[186:189], v[16:19]
	v_mfma_f32_16x16x32_bf16 v[16:19], v[0:3], v[198:201], v[232:235]
	v_mfma_f32_16x16x32_bf16 v[0:3], v[0:3], v[218:221], v[156:159]
	v_mfma_f32_16x16x32_bf16 v[16:19], v[4:7], v[202:205], v[16:19]
	v_mfma_f32_16x16x32_bf16 v[20:23], v[190:193], v[198:201], v[238:241]
	v_mfma_f32_16x16x32_bf16 v[0:3], v[4:7], v[142:145], v[0:3]
	v_mfma_f32_16x16x32_bf16 v[4:7], v[190:193], v[218:221], v[160:163]
	v_mfma_f32_16x16x32_bf16 v[20:23], v[194:197], v[202:205], v[20:23]
	v_mfma_f32_16x16x32_bf16 v[4:7], v[194:197], v[142:145], v[4:7]
	s_setprio 0
	s_setprio 1
	v_mfma_f32_16x16x32_bf16 v[24:27], v[222:225], v[92:95], v[24:27]
	v_mfma_f32_16x16x32_bf16 v[28:31], v[210:213], v[92:95], v[28:31]
	v_mfma_f32_16x16x32_bf16 v[92:95], v[242:245], v[178:181], v[24:27]
	v_mfma_f32_16x16x32_bf16 v[24:27], v[210:213], v[182:185], v[164:167]
	v_mfma_f32_16x16x32_bf16 v[56:59], v[214:217], v[186:189], v[24:27]
	v_mfma_f32_16x16x32_bf16 v[24:27], v[222:225], v[182:185], v[168:171]
	v_mfma_f32_16x16x32_bf16 v[12:15], v[210:213], v[198:201], v[12:15]
	v_mfma_f32_16x16x32_bf16 v[8:11], v[222:225], v[198:201], v[8:11]
	v_mfma_f32_16x16x32_bf16 v[88:91], v[214:217], v[178:181], v[28:31]
	v_mfma_f32_16x16x32_bf16 v[60:63], v[242:245], v[186:189], v[24:27]
	v_mfma_f32_16x16x32_bf16 v[24:27], v[214:217], v[202:205], v[12:15]
	v_mfma_f32_16x16x32_bf16 v[28:31], v[242:245], v[202:205], v[8:11]
	v_mfma_f32_16x16x32_bf16 v[8:11], v[210:213], v[218:221], v[172:175]
	v_mfma_f32_16x16x32_bf16 v[12:15], v[222:225], v[218:221], v[146:149]
	v_mfma_f32_16x16x32_bf16 v[8:11], v[214:217], v[142:145], v[8:11]
	v_mfma_f32_16x16x32_bf16 v[12:15], v[242:245], v[142:145], v[12:15]
	s_setprio 0
	s_cmpk_lt_u32 s9, 0x100
	s_barrier
	s_cbranch_scc0 .LBB0_66
	s_barrier

.LBB0_105:
	ds_read_b128 v[148:151], v145 offset:0
	ds_read_b128 v[152:155], v145 offset:1024
	ds_read_b128 v[160:163], v145 offset:2048
	ds_read_b128 v[164:167], v145 offset:3072
	s_add_u32 s35, s1, s40
	s_addc_u32 s43, s26, s41
	s_add_u32 s42, s35, 0x80
	v_add_u32_e32 v158, 0xc000, v134
	s_addc_u32 s43, s43, 0
	v_readfirstlane_b32 s35, v158
	v_add_u32_e32 v159, 0xe000, v134
	s_mov_b32 m0, s35
	ds_read_b128 v[168:171], v144 offset:0
	ds_read_b128 v[172:175], v144 offset:1024
	ds_read_b128 v[178:181], v144 offset:2048
	ds_read_b128 v[182:185], v144 offset:3072
	ds_read_b128 v[186:189], v144 offset:4096
	ds_read_b128 v[190:193], v144 offset:5120
	ds_read_b128 v[194:197], v144 offset:6144
	ds_read_b128 v[198:201], v144 offset:7168
	global_load_lds_dwordx4 v128, s[42:43]
	s_add_u32 m0, m0, 0x2000
	s_nop 0
	global_load_lds_dwordx4 v130, s[42:43]
	ds_read_b128 v[202:205], v143 offset:0
	ds_read_b128 v[206:209], v143 offset:1024
	ds_read_b128 v[210:213], v143 offset:2048
	ds_read_b128 v[214:217], v143 offset:3072
	s_waitcnt vmcnt(8)
	s_waitcnt lgkmcnt(0)
	s_barrier
	s_waitcnt lgkmcnt(0)
	s_waitcnt lgkmcnt(0)
	s_setprio 1
	v_mfma_f32_16x16x32_bf16 v[124:127], v[148:151], v[168:171], v[124:127]
	v_mfma_f32_16x16x32_bf16 v[120:123], v[160:163], v[168:171], v[120:123]
	v_mfma_f32_16x16x32_bf16 v[116:119], v[148:151], v[178:181], v[116:119]
	v_mfma_f32_16x16x32_bf16 v[112:115], v[160:163], v[178:181], v[112:115]
	v_mfma_f32_16x16x32_bf16 v[108:111], v[148:151], v[186:189], v[108:111]
	v_mfma_f32_16x16x32_bf16 v[104:107], v[160:163], v[186:189], v[104:107]
	v_mfma_f32_16x16x32_bf16 v[100:103], v[148:151], v[194:197], v[100:103]
	v_mfma_f32_16x16x32_bf16 v[96:99], v[160:163], v[194:197], v[96:99]
	v_mfma_f32_16x16x32_bf16 v[124:127], v[152:155], v[172:175], v[124:127]
	v_mfma_f32_16x16x32_bf16 v[120:123], v[164:167], v[172:175], v[120:123]
	v_mfma_f32_16x16x32_bf16 v[116:119], v[152:155], v[182:185], v[116:119]
	v_mfma_f32_16x16x32_bf16 v[112:115], v[164:167], v[182:185], v[112:115]
	v_mfma_f32_16x16x32_bf16 v[108:111], v[152:155], v[190:193], v[108:111]
	v_mfma_f32_16x16x32_bf16 v[104:107], v[164:167], v[190:193], v[104:107]
	v_mfma_f32_16x16x32_bf16 v[100:103], v[152:155], v[198:201], v[100:103]
	v_mfma_f32_16x16x32_bf16 v[96:99], v[164:167], v[198:201], v[96:99]
	s_setprio 0
	s_waitcnt lgkmcnt(0)
	s_setprio 1
	v_mfma_f32_16x16x32_bf16 v[92:95], v[202:205], v[168:171], v[92:95]
	v_mfma_f32_16x16x32_bf16 v[88:91], v[210:213], v[168:171], v[88:91]
	v_mfma_f32_16x16x32_bf16 v[84:87], v[202:205], v[178:181], v[84:87]
	v_mfma_f32_16x16x32_bf16 v[80:83], v[210:213], v[178:181], v[80:83]
	v_mfma_f32_16x16x32_bf16 v[76:79], v[202:205], v[186:189], v[76:79]
	v_mfma_f32_16x16x32_bf16 v[72:75], v[210:213], v[186:189], v[72:75]
	v_mfma_f32_16x16x32_bf16 v[68:71], v[202:205], v[194:197], v[68:71]
	v_mfma_f32_16x16x32_bf16 v[64:67], v[210:213], v[194:197], v[64:67]
	v_mfma_f32_16x16x32_bf16 v[92:95], v[206:209], v[172:175], v[92:95]
	v_mfma_f32_16x16x32_bf16 v[88:91], v[214:217], v[172:175], v[88:91]
	v_mfma_f32_16x16x32_bf16 v[84:87], v[206:209], v[182:185], v[84:87]
	v_mfma_f32_16x16x32_bf16 v[80:83], v[214:217], v[182:185], v[80:83]
	v_mfma_f32_16x16x32_bf16 v[76:79], v[206:209], v[190:193], v[76:79]
	v_mfma_f32_16x16x32_bf16 v[72:75], v[214:217], v[190:193], v[72:75]
	v_mfma_f32_16x16x32_bf16 v[68:71], v[206:209], v[198:201], v[68:71]
	v_mfma_f32_16x16x32_bf16 v[64:67], v[214:217], v[198:201], v[64:67]
	s_setprio 0
	s_barrier
	s_add_u32 s35, s2, s40
	s_addc_u32 s45, s3, s41
	s_add_u32 s42, s35, 0x100
	v_add_u32_e32 v146, 0x10000, v134
	s_addc_u32 s43, s45, 0
	v_readfirstlane_b32 s51, v146
	s_mov_b32 m0, s51
	v_add_u32_e32 v147, 0x12000, v134
	global_load_lds_dwordx4 v176, s[42:43]
	s_add_u32 m0, m0, 0x2000
	s_nop 0
	global_load_lds_dwordx4 v132, s[42:43]
	s_add_u32 s51, s20, s40
	s_addc_u32 s54, s21, s41
	s_add_u32 s42, s51, 0x100
	s_addc_u32 s43, s54, 0
	v_readfirstlane_b32 s88, v134
	s_mov_b32 m0, s88
	ds_read_b128 v[168:171], v142 offset:0
	ds_read_b128 v[172:175], v142 offset:1024
	ds_read_b128 v[178:181], v142 offset:2048
	ds_read_b128 v[182:185], v142 offset:3072
	ds_read_b128 v[186:189], v142 offset:4096
	ds_read_b128 v[190:193], v142 offset:5120
	ds_read_b128 v[194:197], v142 offset:6144
	ds_read_b128 v[198:201], v142 offset:7168
	global_load_lds_dwordx4 v128, s[42:43]
	s_add_u32 m0, m0, 0x2000
	s_nop 0
	global_load_lds_dwordx4 v130, s[42:43]
	s_add_u32 s88, s27, s40
	s_addc_u32 s89, s28, s41
	s_add_u32 s42, s88, 0x100
	v_add_u32_e32 v226, 0x14000, v134
	s_addc_u32 s43, s89, 0
	v_readfirstlane_b32 s96, v226
	s_mov_b32 m0, s96
	v_add_u32_e32 v227, 0x16000, v134
	global_load_lds_dwordx4 v176, s[42:43]
	s_add_u32 m0, m0, 0x2000
	s_nop 0
	global_load_lds_dwordx4 v132, s[42:43]
	s_waitcnt vmcnt(8)
	s_waitcnt lgkmcnt(0)
	s_barrier
	s_waitcnt lgkmcnt(0)
	s_setprio 1
	v_mfma_f32_16x16x32_bf16 v[60:63], v[148:151], v[168:171], v[60:63]
	v_mfma_f32_16x16x32_bf16 v[56:59], v[160:163], v[168:171], v[56:59]
	v_mfma_f32_16x16x32_bf16 v[52:55], v[148:151], v[178:181], v[52:55]
	v_mfma_f32_16x16x32_bf16 v[48:51], v[160:163], v[178:181], v[48:51]
	v_mfma_f32_16x16x32_bf16 v[44:47], v[148:151], v[186:189], v[44:47]
	v_mfma_f32_16x16x32_bf16 v[40:43], v[160:163], v[186:189], v[40:43]
	v_mfma_f32_16x16x32_bf16 v[36:39], v[148:151], v[194:197], v[36:39]
	v_mfma_f32_16x16x32_bf16 v[32:35], v[160:163], v[194:197], v[32:35]
	v_mfma_f32_16x16x32_bf16 v[60:63], v[152:155], v[172:175], v[60:63]
	v_mfma_f32_16x16x32_bf16 v[56:59], v[164:167], v[172:175], v[56:59]
	v_mfma_f32_16x16x32_bf16 v[52:55], v[152:155], v[182:185], v[52:55]
	v_mfma_f32_16x16x32_bf16 v[48:51], v[164:167], v[182:185], v[48:51]
	v_mfma_f32_16x16x32_bf16 v[44:47], v[152:155], v[190:193], v[44:47]
	v_mfma_f32_16x16x32_bf16 v[40:43], v[164:167], v[190:193], v[40:43]
	v_mfma_f32_16x16x32_bf16 v[36:39], v[152:155], v[198:201], v[36:39]
	v_mfma_f32_16x16x32_bf16 v[32:35], v[164:167], v[198:201], v[32:35]
	s_setprio 0
	s_setprio 1
	v_mfma_f32_16x16x32_bf16 v[28:31], v[202:205], v[168:171], v[28:31]
	v_mfma_f32_16x16x32_bf16 v[24:27], v[210:213], v[168:171], v[24:27]
	v_mfma_f32_16x16x32_bf16 v[20:23], v[202:205], v[178:181], v[20:23]
	v_mfma_f32_16x16x32_bf16 v[16:19], v[210:213], v[178:181], v[16:19]
	v_mfma_f32_16x16x32_bf16 v[12:15], v[202:205], v[186:189], v[12:15]
	v_mfma_f32_16x16x32_bf16 v[8:11], v[210:213], v[186:189], v[8:11]
	v_mfma_f32_16x16x32_bf16 v[4:7], v[202:205], v[194:197], v[4:7]
	v_mfma_f32_16x16x32_bf16 v[0:3], v[210:213], v[194:197], v[0:3]
	v_mfma_f32_16x16x32_bf16 v[28:31], v[206:209], v[172:175], v[28:31]
	v_mfma_f32_16x16x32_bf16 v[24:27], v[214:217], v[172:175], v[24:27]
	v_mfma_f32_16x16x32_bf16 v[20:23], v[206:209], v[182:185], v[20:23]
	v_mfma_f32_16x16x32_bf16 v[16:19], v[214:217], v[182:185], v[16:19]
	v_mfma_f32_16x16x32_bf16 v[12:15], v[206:209], v[190:193], v[12:15]
	v_mfma_f32_16x16x32_bf16 v[8:11], v[214:217], v[190:193], v[8:11]
	v_mfma_f32_16x16x32_bf16 v[4:7], v[206:209], v[198:201], v[4:7]
	v_mfma_f32_16x16x32_bf16 v[0:3], v[214:217], v[198:201], v[0:3]
	s_setprio 0
	s_barrier
	ds_read_b128 v[160:163], v141 offset:0
	ds_read_b128 v[164:167], v141 offset:1024
	ds_read_b128 v[168:171], v141 offset:2048
	ds_read_b128 v[172:175], v141 offset:3072
	s_add_u32 s42, s29, s40
	v_add_u32_e32 v150, 0x4000, v134
	s_addc_u32 s43, s30, s41
	v_readfirstlane_b32 s96, v150
	s_mov_b32 m0, s96
	v_add_u32_e32 v151, 0x6000, v134
	ds_read_b128 v[154:157], v140 offset:0
	ds_read_b128 v[178:181], v140 offset:1024
	ds_read_b128 v[182:185], v140 offset:2048
	ds_read_b128 v[186:189], v140 offset:3072
	ds_read_b128 v[190:193], v140 offset:4096
	ds_read_b128 v[194:197], v140 offset:5120
	ds_read_b128 v[198:201], v140 offset:6144
	ds_read_b128 v[202:205], v140 offset:7168
	global_load_lds_dwordx4 v128, s[42:43]
	s_add_u32 m0, m0, 0x2000
	s_nop 0
	global_load_lds_dwordx4 v130, s[42:43]
	ds_read_b128 v[206:209], v139 offset:0
	ds_read_b128 v[210:213], v139 offset:1024
	ds_read_b128 v[214:217], v139 offset:2048
	ds_read_b128 v[218:221], v139 offset:3072
	s_waitcnt vmcnt(8)
	s_waitcnt lgkmcnt(0)
	s_barrier
	s_waitcnt lgkmcnt(0)
	s_waitcnt lgkmcnt(0)
	s_setprio 1
	v_mfma_f32_16x16x32_bf16 v[124:127], v[160:163], v[154:157], v[124:127]
	v_mfma_f32_16x16x32_bf16 v[120:123], v[168:171], v[154:157], v[120:123]
	v_mfma_f32_16x16x32_bf16 v[116:119], v[160:163], v[182:185], v[116:119]
	v_mfma_f32_16x16x32_bf16 v[112:115], v[168:171], v[182:185], v[112:115]
	v_mfma_f32_16x16x32_bf16 v[108:111], v[160:163], v[190:193], v[108:111]
	v_mfma_f32_16x16x32_bf16 v[104:107], v[168:171], v[190:193], v[104:107]
	v_mfma_f32_16x16x32_bf16 v[100:103], v[160:163], v[198:201], v[100:103]
	v_mfma_f32_16x16x32_bf16 v[96:99], v[168:171], v[198:201], v[96:99]
	v_mfma_f32_16x16x32_bf16 v[124:127], v[164:167], v[178:181], v[124:127]
	v_mfma_f32_16x16x32_bf16 v[120:123], v[172:175], v[178:181], v[120:123]
	v_mfma_f32_16x16x32_bf16 v[116:119], v[164:167], v[186:189], v[116:119]
	v_mfma_f32_16x16x32_bf16 v[112:115], v[172:175], v[186:189], v[112:115]
	v_mfma_f32_16x16x32_bf16 v[108:111], v[164:167], v[194:197], v[108:111]
	v_mfma_f32_16x16x32_bf16 v[104:107], v[172:175], v[194:197], v[104:107]
	v_mfma_f32_16x16x32_bf16 v[100:103], v[164:167], v[202:205], v[100:103]
	v_mfma_f32_16x16x32_bf16 v[96:99], v[172:175], v[202:205], v[96:99]
	s_setprio 0
	s_waitcnt lgkmcnt(0)
	s_setprio 1
	v_mfma_f32_16x16x32_bf16 v[92:95], v[206:209], v[154:157], v[92:95]
	v_mfma_f32_16x16x32_bf16 v[88:91], v[214:217], v[154:157], v[88:91]
	v_mfma_f32_16x16x32_bf16 v[84:87], v[206:209], v[182:185], v[84:87]
	v_mfma_f32_16x16x32_bf16 v[80:83], v[214:217], v[182:185], v[80:83]
	v_mfma_f32_16x16x32_bf16 v[76:79], v[206:209], v[190:193], v[76:79]
	v_mfma_f32_16x16x32_bf16 v[72:75], v[214:217], v[190:193], v[72:75]
	v_mfma_f32_16x16x32_bf16 v[68:71], v[206:209], v[198:201], v[68:71]
	v_mfma_f32_16x16x32_bf16 v[64:67], v[214:217], v[198:201], v[64:67]
	v_mfma_f32_16x16x32_bf16 v[92:95], v[210:213], v[178:181], v[92:95]
	v_mfma_f32_16x16x32_bf16 v[88:91], v[218:221], v[178:181], v[88:91]
	v_mfma_f32_16x16x32_bf16 v[84:87], v[210:213], v[186:189], v[84:87]
	v_mfma_f32_16x16x32_bf16 v[80:83], v[218:221], v[186:189], v[80:83]
	v_mfma_f32_16x16x32_bf16 v[76:79], v[210:213], v[194:197], v[76:79]
	v_mfma_f32_16x16x32_bf16 v[72:75], v[218:221], v[194:197], v[72:75]
	v_mfma_f32_16x16x32_bf16 v[68:71], v[210:213], v[202:205], v[68:71]
	v_mfma_f32_16x16x32_bf16 v[64:67], v[218:221], v[202:205], v[64:67]
	s_setprio 0
	s_barrier
	s_add_u32 s42, s35, 0x180
	v_add_u32_e32 v152, 0x18000, v134
	s_addc_u32 s43, s45, 0
	v_readfirstlane_b32 s35, v152
	v_add_u32_e32 v153, 0x1a000, v134
	s_mov_b32 m0, s35
	global_load_lds_dwordx4 v176, s[42:43]
	s_add_u32 m0, m0, 0x2000
	s_nop 0
	global_load_lds_dwordx4 v132, s[42:43]
	s_add_u32 s42, s51, 0x180
	v_add_u32_e32 v154, 0x8000, v134
	s_addc_u32 s43, s54, 0
	v_readfirstlane_b32 s35, v154
	v_add_u32_e32 v155, 0xa000, v134
	s_mov_b32 m0, s35
	ds_read_b128 v[178:181], v138 offset:0
	ds_read_b128 v[182:185], v138 offset:1024
	ds_read_b128 v[186:189], v138 offset:2048
	ds_read_b128 v[190:193], v138 offset:3072
	ds_read_b128 v[194:197], v138 offset:4096
	ds_read_b128 v[198:201], v138 offset:5120
	ds_read_b128 v[202:205], v138 offset:6144
	ds_read_b128 v[222:225], v138 offset:7168
	global_load_lds_dwordx4 v128, s[42:43]
	s_add_u32 m0, m0, 0x2000
	s_nop 0
	global_load_lds_dwordx4 v130, s[42:43]
	s_add_u32 s42, s88, 0x180
	v_add_u32_e32 v156, 0x1c000, v134
	s_addc_u32 s43, s89, 0
	v_readfirstlane_b32 s35, v156
	v_add_u32_e32 v157, 0x1e000, v134
	s_mov_b32 m0, s35
	global_load_lds_dwordx4 v176, s[42:43]
	s_add_u32 m0, m0, 0x2000
	s_nop 0
	global_load_lds_dwordx4 v132, s[42:43]
	s_waitcnt vmcnt(8)
	s_waitcnt lgkmcnt(0)
	s_barrier
	s_waitcnt lgkmcnt(0)
	s_setprio 1
	v_mfma_f32_16x16x32_bf16 v[60:63], v[160:163], v[178:181], v[60:63]
	v_mfma_f32_16x16x32_bf16 v[56:59], v[168:171], v[178:181], v[56:59]
	v_mfma_f32_16x16x32_bf16 v[52:55], v[160:163], v[186:189], v[52:55]
	v_mfma_f32_16x16x32_bf16 v[48:51], v[168:171], v[186:189], v[48:51]
	v_mfma_f32_16x16x32_bf16 v[44:47], v[160:163], v[194:197], v[44:47]
	v_mfma_f32_16x16x32_bf16 v[40:43], v[168:171], v[194:197], v[40:43]
	v_mfma_f32_16x16x32_bf16 v[36:39], v[160:163], v[202:205], v[36:39]
	v_mfma_f32_16x16x32_bf16 v[32:35], v[168:171], v[202:205], v[32:35]
	v_mfma_f32_16x16x32_bf16 v[60:63], v[164:167], v[182:185], v[60:63]
	v_mfma_f32_16x16x32_bf16 v[56:59], v[172:175], v[182:185], v[56:59]
	v_mfma_f32_16x16x32_bf16 v[52:55], v[164:167], v[190:193], v[52:55]
	v_mfma_f32_16x16x32_bf16 v[48:51], v[172:175], v[190:193], v[48:51]
	v_mfma_f32_16x16x32_bf16 v[44:47], v[164:167], v[198:201], v[44:47]
	v_mfma_f32_16x16x32_bf16 v[40:43], v[172:175], v[198:201], v[40:43]
	v_mfma_f32_16x16x32_bf16 v[36:39], v[164:167], v[222:225], v[36:39]
	v_mfma_f32_16x16x32_bf16 v[32:35], v[172:175], v[222:225], v[32:35]
	s_setprio 0
	s_setprio 1
	v_mfma_f32_16x16x32_bf16 v[28:31], v[206:209], v[178:181], v[28:31]
	v_mfma_f32_16x16x32_bf16 v[24:27], v[214:217], v[178:181], v[24:27]
	v_mfma_f32_16x16x32_bf16 v[20:23], v[206:209], v[186:189], v[20:23]
	v_mfma_f32_16x16x32_bf16 v[16:19], v[214:217], v[186:189], v[16:19]
	v_mfma_f32_16x16x32_bf16 v[12:15], v[206:209], v[194:197], v[12:15]
	v_mfma_f32_16x16x32_bf16 v[8:11], v[214:217], v[194:197], v[8:11]
	v_mfma_f32_16x16x32_bf16 v[4:7], v[206:209], v[202:205], v[4:7]
	v_mfma_f32_16x16x32_bf16 v[0:3], v[214:217], v[202:205], v[0:3]
	v_mfma_f32_16x16x32_bf16 v[28:31], v[210:213], v[182:185], v[28:31]
	v_mfma_f32_16x16x32_bf16 v[24:27], v[218:221], v[182:185], v[24:27]
	v_mfma_f32_16x16x32_bf16 v[20:23], v[210:213], v[190:193], v[20:23]
	v_mfma_f32_16x16x32_bf16 v[16:19], v[218:221], v[190:193], v[16:19]
	v_mfma_f32_16x16x32_bf16 v[12:15], v[210:213], v[198:201], v[12:15]
	v_mfma_f32_16x16x32_bf16 v[8:11], v[218:221], v[198:201], v[8:11]
	v_mfma_f32_16x16x32_bf16 v[4:7], v[210:213], v[222:225], v[4:7]
	v_mfma_f32_16x16x32_bf16 v[0:3], v[218:221], v[222:225], v[0:3]
	s_setprio 0
	s_add_i32 s31, s31, 2
	s_add_u32 s40, s40, 0x100
	s_addc_u32 s41, s41, 0
	s_cmp_gt_u32 s31, 11
	s_barrier
	s_cbranch_scc0 .LBB0_105
	v_add_u32_e32 v158, 0xc000, v134
	v_add_u32_e32 v159, 0xe000, v134
	v_add_u32_e32 v146, 0x10000, v134
	v_add_u32_e32 v147, 0x12000, v134
	v_add_u32_e32 v148, 0x14000, v134
	v_add_u32_e32 v149, 0x16000, v134
	v_add_u32_e32 v150, 0x4000, v134
	v_add_u32_e32 v151, 0x6000, v134
	v_add_u32_e32 v152, 0x18000, v134
	v_add_u32_e32 v153, 0x1a000, v134
	v_add_u32_e32 v154, 0x8000, v134
	v_add_u32_e32 v155, 0xa000, v134
	v_add_u32_e32 v156, 0x1c000, v134
	v_add_u32_e32 v157, 0x1e000, v134
	s_add_u32 s2, s1, 0x780
	s_addc_u32 s3, s26, 0
	v_readfirstlane_b32 s1, v158
	v_lshl_add_u64 v[132:133], s[2:3], 0, v[128:129]
	s_mov_b32 m0, s1
	v_readfirstlane_b32 s1, v159
	ds_read_b128 v[160:163], v145 offset:0
	ds_read_b128 v[164:167], v145 offset:1024
	ds_read_b128 v[168:171], v145 offset:2048
	ds_read_b128 v[172:175], v145 offset:3072
	ds_read_b128 v[178:181], v144 offset:0
	ds_read_b128 v[182:185], v144 offset:1024
	ds_read_b128 v[186:189], v144 offset:2048
	ds_read_b128 v[190:193], v144 offset:3072
	ds_read_b128 v[194:197], v144 offset:4096
	ds_read_b128 v[198:201], v144 offset:5120
	ds_read_b128 v[202:205], v144 offset:6144
	ds_read_b128 v[206:209], v144 offset:7168
	global_load_lds_dwordx4 v[132:133], off
	v_lshl_add_u64 v[132:133], s[2:3], 0, v[130:131]
	s_mov_b32 m0, s1
	s_nop 0
	global_load_lds_dwordx4 v[132:133], off
	s_waitcnt vmcnt(10)
	s_barrier
	s_waitcnt lgkmcnt(0)
	s_waitcnt lgkmcnt(0)
	s_setprio 1
	v_mfma_f32_16x16x32_bf16 v[124:127], v[160:163], v[178:181], v[124:127]
	v_mfma_f32_16x16x32_bf16 v[120:123], v[168:171], v[178:181], v[120:123]
	v_mfma_f32_16x16x32_bf16 v[116:119], v[160:163], v[186:189], v[116:119]
	v_mfma_f32_16x16x32_bf16 v[112:115], v[168:171], v[186:189], v[112:115]
	v_mfma_f32_16x16x32_bf16 v[100:103], v[160:163], v[202:205], v[100:103]
	v_mfma_f32_16x16x32_bf16 v[96:99], v[168:171], v[202:205], v[96:99]
	v_mfma_f32_16x16x32_bf16 v[124:127], v[164:167], v[182:185], v[124:127]
	v_mfma_f32_16x16x32_bf16 v[120:123], v[172:175], v[182:185], v[120:123]
	v_mfma_f32_16x16x32_bf16 v[116:119], v[164:167], v[190:193], v[116:119]
	v_mfma_f32_16x16x32_bf16 v[112:115], v[172:175], v[190:193], v[112:115]
	v_mfma_f32_16x16x32_bf16 v[108:111], v[160:163], v[194:197], v[108:111]
	v_mfma_f32_16x16x32_bf16 v[104:107], v[168:171], v[194:197], v[104:107]
	v_mfma_f32_16x16x32_bf16 v[100:103], v[164:167], v[206:209], v[100:103]
	v_mfma_f32_16x16x32_bf16 v[96:99], v[172:175], v[206:209], v[96:99]
	v_mfma_f32_16x16x32_bf16 v[210:213], v[164:167], v[198:201], v[108:111]
	v_mfma_f32_16x16x32_bf16 v[214:217], v[172:175], v[198:201], v[104:107]
	s_setprio 0
	s_barrier
	ds_read_b128 v[104:107], v143 offset:0
	ds_read_b128 v[108:111], v143 offset:1024
	ds_read_b128 v[218:221], v143 offset:2048
	ds_read_b128 v[222:225], v143 offset:3072
	s_waitcnt vmcnt(8)
	s_barrier
	s_waitcnt lgkmcnt(0)
	s_setprio 1
	v_mfma_f32_16x16x32_bf16 v[92:95], v[104:107], v[178:181], v[92:95]
	v_mfma_f32_16x16x32_bf16 v[88:91], v[218:221], v[178:181], v[88:91]
	v_mfma_f32_16x16x32_bf16 v[76:79], v[104:107], v[194:197], v[76:79]
	v_mfma_f32_16x16x32_bf16 v[72:75], v[218:221], v[194:197], v[72:75]
	v_mfma_f32_16x16x32_bf16 v[68:71], v[104:107], v[202:205], v[68:71]
	v_mfma_f32_16x16x32_bf16 v[92:95], v[108:111], v[182:185], v[92:95]
	v_mfma_f32_16x16x32_bf16 v[88:91], v[222:225], v[182:185], v[88:91]
	v_mfma_f32_16x16x32_bf16 v[84:87], v[104:107], v[186:189], v[84:87]
	v_mfma_f32_16x16x32_bf16 v[80:83], v[218:221], v[186:189], v[80:83]
	v_mfma_f32_16x16x32_bf16 v[76:79], v[108:111], v[198:201], v[76:79]
	v_mfma_f32_16x16x32_bf16 v[72:75], v[222:225], v[198:201], v[72:75]
	v_mfma_f32_16x16x32_bf16 v[68:71], v[108:111], v[206:209], v[68:71]
	v_mfma_f32_16x16x32_bf16 v[64:67], v[218:221], v[202:205], v[64:67]
	v_mfma_f32_16x16x32_bf16 v[178:181], v[108:111], v[190:193], v[84:87]
	v_mfma_f32_16x16x32_bf16 v[182:185], v[222:225], v[190:193], v[80:83]
	v_mfma_f32_16x16x32_bf16 v[186:189], v[222:225], v[206:209], v[64:67]
	s_setprio 0
	s_barrier
	ds_read_b128 v[64:67], v142 offset:0
	ds_read_b128 v[80:83], v142 offset:1024
	ds_read_b128 v[84:87], v142 offset:2048
	ds_read_b128 v[190:193], v142 offset:3072
	ds_read_b128 v[194:197], v142 offset:4096
	ds_read_b128 v[198:201], v142 offset:5120
	ds_read_b128 v[202:205], v142 offset:6144
	ds_read_b128 v[142:145], v142 offset:7168
	s_waitcnt vmcnt(4)
	s_barrier
	s_waitcnt lgkmcnt(0)
	s_setprio 1
	s_nop 0
	v_mfma_f32_16x16x32_bf16 v[60:63], v[160:163], v[64:67], v[60:63]
	v_mfma_f32_16x16x32_bf16 v[56:59], v[168:171], v[64:67], v[56:59]
	v_mfma_f32_16x16x32_bf16 v[60:63], v[164:167], v[80:83], v[60:63]
	v_mfma_f32_16x16x32_bf16 v[56:59], v[172:175], v[80:83], v[56:59]
	v_mfma_f32_16x16x32_bf16 v[52:55], v[160:163], v[84:87], v[52:55]
	v_mfma_f32_16x16x32_bf16 v[48:51], v[168:171], v[84:87], v[48:51]
	v_mfma_f32_16x16x32_bf16 v[44:47], v[160:163], v[194:197], v[44:47]
	v_mfma_f32_16x16x32_bf16 v[40:43], v[168:171], v[194:197], v[40:43]
	v_mfma_f32_16x16x32_bf16 v[36:39], v[160:163], v[202:205], v[36:39]
	v_mfma_f32_16x16x32_bf16 v[32:35], v[168:171], v[202:205], v[32:35]
	v_mfma_f32_16x16x32_bf16 v[206:209], v[164:167], v[190:193], v[52:55]
	v_mfma_f32_16x16x32_bf16 v[226:229], v[172:175], v[190:193], v[48:51]
	v_mfma_f32_16x16x32_bf16 v[232:235], v[164:167], v[198:201], v[44:47]
	v_mfma_f32_16x16x32_bf16 v[238:241], v[172:175], v[198:201], v[40:43]
	v_mfma_f32_16x16x32_bf16 v[158:161], v[164:167], v[142:145], v[36:39]
	v_mfma_f32_16x16x32_bf16 v[162:165], v[172:175], v[142:145], v[32:35]
	s_setprio 0
	s_setprio 1
	v_mfma_f32_16x16x32_bf16 v[28:31], v[104:107], v[64:67], v[28:31]
	v_mfma_f32_16x16x32_bf16 v[24:27], v[218:221], v[64:67], v[24:27]
	v_mfma_f32_16x16x32_bf16 v[12:15], v[104:107], v[194:197], v[12:15]
	v_mfma_f32_16x16x32_bf16 v[8:11], v[218:221], v[194:197], v[8:11]
	v_mfma_f32_16x16x32_bf16 v[28:31], v[108:111], v[80:83], v[28:31]
	v_mfma_f32_16x16x32_bf16 v[24:27], v[222:225], v[80:83], v[24:27]
	v_mfma_f32_16x16x32_bf16 v[20:23], v[104:107], v[84:87], v[20:23]
	v_mfma_f32_16x16x32_bf16 v[16:19], v[218:221], v[84:87], v[16:19]
	v_mfma_f32_16x16x32_bf16 v[12:15], v[108:111], v[198:201], v[12:15]
	v_mfma_f32_16x16x32_bf16 v[8:11], v[222:225], v[198:201], v[8:11]
	v_mfma_f32_16x16x32_bf16 v[4:7], v[104:107], v[202:205], v[4:7]
	v_mfma_f32_16x16x32_bf16 v[0:3], v[218:221], v[202:205], v[0:3]
	v_mfma_f32_16x16x32_bf16 v[166:169], v[108:111], v[190:193], v[20:23]
	v_mfma_f32_16x16x32_bf16 v[170:173], v[222:225], v[190:193], v[16:19]
	v_mfma_f32_16x16x32_bf16 v[190:193], v[108:111], v[142:145], v[4:7]
	v_mfma_f32_16x16x32_bf16 v[142:145], v[222:225], v[142:145], v[0:3]
	s_setprio 0
	s_barrier
	ds_read_b128 v[0:3], v141 offset:0
	ds_read_b128 v[4:7], v141 offset:1024
	ds_read_b128 v[194:197], v141 offset:2048
	ds_read_b128 v[198:201], v141 offset:3072
	ds_read_b128 v[16:19], v140 offset:0
	ds_read_b128 v[20:23], v140 offset:1024
	ds_read_b128 v[40:43], v140 offset:2048
	ds_read_b128 v[44:47], v140 offset:3072
	ds_read_b128 v[64:67], v140 offset:4096
	ds_read_b128 v[202:205], v140 offset:5120
	ds_read_b128 v[218:221], v140 offset:6144
	ds_read_b128 v[222:225], v140 offset:7168
	s_waitcnt vmcnt(2)
	s_barrier
	s_waitcnt lgkmcnt(0)
	s_waitcnt lgkmcnt(0)
	s_setprio 1
	v_mfma_f32_16x16x32_bf16 v[32:35], v[0:3], v[16:19], v[124:127]
	v_mfma_f32_16x16x32_bf16 v[104:107], v[4:7], v[20:23], v[32:35]
	v_mfma_f32_16x16x32_bf16 v[32:35], v[194:197], v[16:19], v[120:123]
	v_mfma_f32_16x16x32_bf16 v[108:111], v[198:201], v[20:23], v[32:35]
	v_mfma_f32_16x16x32_bf16 v[32:35], v[0:3], v[40:43], v[116:119]
	v_mfma_f32_16x16x32_bf16 v[80:83], v[4:7], v[44:47], v[32:35]
	v_mfma_f32_16x16x32_bf16 v[32:35], v[194:197], v[40:43], v[112:115]
	v_mfma_f32_16x16x32_bf16 v[84:87], v[198:201], v[44:47], v[32:35]
	v_mfma_f32_16x16x32_bf16 v[32:35], v[0:3], v[64:67], v[210:213]
	v_mfma_f32_16x16x32_bf16 v[48:51], v[4:7], v[202:205], v[32:35]
	v_mfma_f32_16x16x32_bf16 v[32:35], v[194:197], v[64:67], v[214:217]
	v_mfma_f32_16x16x32_bf16 v[52:55], v[198:201], v[202:205], v[32:35]
	v_mfma_f32_16x16x32_bf16 v[32:35], v[0:3], v[218:221], v[100:103]
	v_mfma_f32_16x16x32_bf16 v[36:39], v[194:197], v[218:221], v[96:99]
	v_mfma_f32_16x16x32_bf16 v[32:35], v[4:7], v[222:225], v[32:35]
	v_mfma_f32_16x16x32_bf16 v[36:39], v[198:201], v[222:225], v[36:39]
	s_setprio 0
	s_barrier
	ds_read_b128 v[210:213], v139 offset:0
	ds_read_b128 v[214:217], v139 offset:1024
	ds_read_b128 v[242:245], v139 offset:2048
	ds_read_b128 v[246:249], v139 offset:3072
	s_waitcnt vmcnt(0)
	s_barrier
	s_waitcnt lgkmcnt(0)
	s_setprio 1
	v_mfma_f32_16x16x32_bf16 v[92:95], v[210:213], v[16:19], v[92:95]
	v_mfma_f32_16x16x32_bf16 v[16:19], v[242:245], v[16:19], v[88:91]
	v_mfma_f32_16x16x32_bf16 v[124:127], v[246:249], v[20:23], v[16:19]
	v_mfma_f32_16x16x32_bf16 v[16:19], v[210:213], v[40:43], v[178:181]
	v_mfma_f32_16x16x32_bf16 v[112:115], v[214:217], v[44:47], v[16:19]
	v_mfma_f32_16x16x32_bf16 v[16:19], v[242:245], v[40:43], v[182:185]
	v_mfma_f32_16x16x32_bf16 v[116:119], v[246:249], v[44:47], v[16:19]
	v_mfma_f32_16x16x32_bf16 v[16:19], v[210:213], v[64:67], v[76:79]
	v_mfma_f32_16x16x32_bf16 v[96:99], v[214:217], v[202:205], v[16:19]
	v_mfma_f32_16x16x32_bf16 v[16:19], v[242:245], v[64:67], v[72:75]
	v_mfma_f32_16x16x32_bf16 v[100:103], v[246:249], v[202:205], v[16:19]
	v_mfma_f32_16x16x32_bf16 v[16:19], v[210:213], v[218:221], v[68:71]
	v_mfma_f32_16x16x32_bf16 v[64:67], v[214:217], v[222:225], v[16:19]
	v_mfma_f32_16x16x32_bf16 v[16:19], v[242:245], v[218:221], v[186:189]
	v_mfma_f32_16x16x32_bf16 v[120:123], v[214:217], v[20:23], v[92:95]
	v_mfma_f32_16x16x32_bf16 v[68:71], v[246:249], v[222:225], v[16:19]
	s_setprio 0
	s_barrier
	ds_read_b128 v[92:95], v138 offset:0
	ds_read_b128 v[178:181], v138 offset:1024
	ds_read_b128 v[182:185], v138 offset:2048
	ds_read_b128 v[186:189], v138 offset:3072
	ds_read_b128 v[202:205], v138 offset:4096
	ds_read_b128 v[218:221], v138 offset:5120
	ds_read_b128 v[222:225], v138 offset:6144
	ds_read_b128 v[138:141], v138 offset:7168
	s_barrier
	s_waitcnt lgkmcnt(0)
	s_setprio 1
	v_mfma_f32_16x16x32_bf16 v[16:19], v[0:3], v[92:95], v[60:63]
	v_mfma_f32_16x16x32_bf16 v[72:75], v[4:7], v[178:181], v[16:19]
	v_mfma_f32_16x16x32_bf16 v[16:19], v[194:197], v[92:95], v[56:59]
	v_mfma_f32_16x16x32_bf16 v[76:79], v[198:201], v[178:181], v[16:19]
	v_mfma_f32_16x16x32_bf16 v[16:19], v[0:3], v[182:185], v[206:209]
	v_mfma_f32_16x16x32_bf16 v[40:43], v[4:7], v[186:189], v[16:19]
	v_mfma_f32_16x16x32_bf16 v[16:19], v[194:197], v[182:185], v[226:229]
	v_mfma_f32_16x16x32_bf16 v[44:47], v[198:201], v[186:189], v[16:19]
	v_mfma_f32_16x16x32_bf16 v[16:19], v[0:3], v[202:205], v[232:235]
	v_mfma_f32_16x16x32_bf16 v[0:3], v[0:3], v[222:225], v[158:161]
	v_mfma_f32_16x16x32_bf16 v[16:19], v[4:7], v[218:221], v[16:19]
	v_mfma_f32_16x16x32_bf16 v[20:23], v[194:197], v[202:205], v[238:241]
	v_mfma_f32_16x16x32_bf16 v[0:3], v[4:7], v[138:141], v[0:3]
	v_mfma_f32_16x16x32_bf16 v[4:7], v[194:197], v[222:225], v[162:165]
	v_mfma_f32_16x16x32_bf16 v[20:23], v[198:201], v[218:221], v[20:23]
	v_mfma_f32_16x16x32_bf16 v[4:7], v[198:201], v[138:141], v[4:7]
	s_setprio 0
	s_setprio 1
	v_mfma_f32_16x16x32_bf16 v[24:27], v[242:245], v[92:95], v[24:27]
	v_mfma_f32_16x16x32_bf16 v[28:31], v[210:213], v[92:95], v[28:31]
	v_mfma_f32_16x16x32_bf16 v[92:95], v[246:249], v[178:181], v[24:27]
	v_mfma_f32_16x16x32_bf16 v[24:27], v[210:213], v[182:185], v[166:169]
	v_mfma_f32_16x16x32_bf16 v[56:59], v[214:217], v[186:189], v[24:27]
	v_mfma_f32_16x16x32_bf16 v[24:27], v[242:245], v[182:185], v[170:173]
	v_mfma_f32_16x16x32_bf16 v[12:15], v[210:213], v[202:205], v[12:15]
	v_mfma_f32_16x16x32_bf16 v[8:11], v[242:245], v[202:205], v[8:11]
	v_mfma_f32_16x16x32_bf16 v[88:91], v[214:217], v[178:181], v[28:31]
	v_mfma_f32_16x16x32_bf16 v[60:63], v[246:249], v[186:189], v[24:27]
	v_mfma_f32_16x16x32_bf16 v[24:27], v[214:217], v[218:221], v[12:15]
	v_mfma_f32_16x16x32_bf16 v[28:31], v[246:249], v[218:221], v[8:11]
	v_mfma_f32_16x16x32_bf16 v[8:11], v[210:213], v[222:225], v[190:193]
	v_mfma_f32_16x16x32_bf16 v[12:15], v[242:245], v[222:225], v[142:145]
	v_mfma_f32_16x16x32_bf16 v[8:11], v[214:217], v[138:141], v[8:11]
	v_mfma_f32_16x16x32_bf16 v[12:15], v[246:249], v[138:141], v[12:15]
	s_setprio 0
	s_cmpk_lt_u32 s11, 0x100
	s_barrier
	s_cbranch_scc0 .LBB0_108
	s_barrier

.LBB0_141:
	ds_read_b128 v[148:151], v145 offset:0
	ds_read_b128 v[152:155], v145 offset:1024
	ds_read_b128 v[160:163], v145 offset:2048
	ds_read_b128 v[164:167], v145 offset:3072
	s_add_u32 s35, s1, s38
	s_addc_u32 s41, s26, s39
	s_add_u32 s40, s35, 0x80
	v_add_u32_e32 v158, 0xc000, v134
	s_addc_u32 s41, s41, 0
	v_readfirstlane_b32 s35, v158
	v_add_u32_e32 v159, 0xe000, v134
	s_mov_b32 m0, s35
	ds_read_b128 v[168:171], v144 offset:0
	ds_read_b128 v[172:175], v144 offset:1024
	ds_read_b128 v[178:181], v144 offset:2048
	ds_read_b128 v[182:185], v144 offset:3072
	ds_read_b128 v[186:189], v144 offset:4096
	ds_read_b128 v[190:193], v144 offset:5120
	ds_read_b128 v[194:197], v144 offset:6144
	ds_read_b128 v[198:201], v144 offset:7168
	global_load_lds_dwordx4 v128, s[40:41]
	s_add_u32 m0, m0, 0x2000
	s_nop 0
	global_load_lds_dwordx4 v130, s[40:41]
	ds_read_b128 v[202:205], v143 offset:0
	ds_read_b128 v[206:209], v143 offset:1024
	ds_read_b128 v[210:213], v143 offset:2048
	ds_read_b128 v[214:217], v143 offset:3072
	s_waitcnt vmcnt(8)
	s_waitcnt lgkmcnt(0)
	s_barrier
	s_waitcnt lgkmcnt(0)
	s_waitcnt lgkmcnt(0)
	s_setprio 1
	v_mfma_f32_16x16x32_bf16 v[124:127], v[148:151], v[168:171], v[124:127]
	v_mfma_f32_16x16x32_bf16 v[120:123], v[160:163], v[168:171], v[120:123]
	v_mfma_f32_16x16x32_bf16 v[116:119], v[148:151], v[178:181], v[116:119]
	v_mfma_f32_16x16x32_bf16 v[112:115], v[160:163], v[178:181], v[112:115]
	v_mfma_f32_16x16x32_bf16 v[108:111], v[148:151], v[186:189], v[108:111]
	v_mfma_f32_16x16x32_bf16 v[104:107], v[160:163], v[186:189], v[104:107]
	v_mfma_f32_16x16x32_bf16 v[100:103], v[148:151], v[194:197], v[100:103]
	v_mfma_f32_16x16x32_bf16 v[96:99], v[160:163], v[194:197], v[96:99]
	v_mfma_f32_16x16x32_bf16 v[124:127], v[152:155], v[172:175], v[124:127]
	v_mfma_f32_16x16x32_bf16 v[120:123], v[164:167], v[172:175], v[120:123]
	v_mfma_f32_16x16x32_bf16 v[116:119], v[152:155], v[182:185], v[116:119]
	v_mfma_f32_16x16x32_bf16 v[112:115], v[164:167], v[182:185], v[112:115]
	v_mfma_f32_16x16x32_bf16 v[108:111], v[152:155], v[190:193], v[108:111]
	v_mfma_f32_16x16x32_bf16 v[104:107], v[164:167], v[190:193], v[104:107]
	v_mfma_f32_16x16x32_bf16 v[100:103], v[152:155], v[198:201], v[100:103]
	v_mfma_f32_16x16x32_bf16 v[96:99], v[164:167], v[198:201], v[96:99]
	s_setprio 0
	s_waitcnt lgkmcnt(0)
	s_setprio 1
	v_mfma_f32_16x16x32_bf16 v[92:95], v[202:205], v[168:171], v[92:95]
	v_mfma_f32_16x16x32_bf16 v[88:91], v[210:213], v[168:171], v[88:91]
	v_mfma_f32_16x16x32_bf16 v[84:87], v[202:205], v[178:181], v[84:87]
	v_mfma_f32_16x16x32_bf16 v[80:83], v[210:213], v[178:181], v[80:83]
	v_mfma_f32_16x16x32_bf16 v[76:79], v[202:205], v[186:189], v[76:79]
	v_mfma_f32_16x16x32_bf16 v[72:75], v[210:213], v[186:189], v[72:75]
	v_mfma_f32_16x16x32_bf16 v[68:71], v[202:205], v[194:197], v[68:71]
	v_mfma_f32_16x16x32_bf16 v[64:67], v[210:213], v[194:197], v[64:67]
	v_mfma_f32_16x16x32_bf16 v[92:95], v[206:209], v[172:175], v[92:95]
	v_mfma_f32_16x16x32_bf16 v[88:91], v[214:217], v[172:175], v[88:91]
	v_mfma_f32_16x16x32_bf16 v[84:87], v[206:209], v[182:185], v[84:87]
	v_mfma_f32_16x16x32_bf16 v[80:83], v[214:217], v[182:185], v[80:83]
	v_mfma_f32_16x16x32_bf16 v[76:79], v[206:209], v[190:193], v[76:79]
	v_mfma_f32_16x16x32_bf16 v[72:75], v[214:217], v[190:193], v[72:75]
	v_mfma_f32_16x16x32_bf16 v[68:71], v[206:209], v[198:201], v[68:71]
	v_mfma_f32_16x16x32_bf16 v[64:67], v[214:217], v[198:201], v[64:67]
	s_setprio 0
	s_barrier
	s_add_u32 s35, s27, s38
	s_addc_u32 s42, s28, s39
	s_add_u32 s40, s35, 0x100
	v_add_u32_e32 v146, 0x10000, v134
	s_addc_u32 s41, s42, 0
	v_readfirstlane_b32 s43, v146
	s_mov_b32 m0, s43
	v_add_u32_e32 v147, 0x12000, v134
	global_load_lds_dwordx4 v176, s[40:41]
	s_add_u32 m0, m0, 0x2000
	s_nop 0
	global_load_lds_dwordx4 v132, s[40:41]
	s_add_u32 s43, s2, s38
	s_addc_u32 s45, s3, s39
	s_add_u32 s40, s43, 0x100
	s_addc_u32 s41, s45, 0
	v_readfirstlane_b32 s48, v134
	s_mov_b32 m0, s48
	ds_read_b128 v[168:171], v142 offset:0
	ds_read_b128 v[172:175], v142 offset:1024
	ds_read_b128 v[178:181], v142 offset:2048
	ds_read_b128 v[182:185], v142 offset:3072
	ds_read_b128 v[186:189], v142 offset:4096
	ds_read_b128 v[190:193], v142 offset:5120
	ds_read_b128 v[194:197], v142 offset:6144
	ds_read_b128 v[198:201], v142 offset:7168
	global_load_lds_dwordx4 v128, s[40:41]
	s_add_u32 m0, m0, 0x2000
	s_nop 0
	global_load_lds_dwordx4 v130, s[40:41]
	s_add_u32 s48, s20, s38
	s_addc_u32 s49, s21, s39
	s_add_u32 s40, s48, 0x100
	v_add_u32_e32 v226, 0x14000, v134
	s_addc_u32 s41, s49, 0
	v_readfirstlane_b32 s51, v226
	s_mov_b32 m0, s51
	v_add_u32_e32 v227, 0x16000, v134
	global_load_lds_dwordx4 v176, s[40:41]
	s_add_u32 m0, m0, 0x2000
	s_nop 0
	global_load_lds_dwordx4 v132, s[40:41]
	s_waitcnt vmcnt(8)
	s_waitcnt lgkmcnt(0)
	s_barrier
	s_waitcnt lgkmcnt(0)
	s_setprio 1
	v_mfma_f32_16x16x32_bf16 v[60:63], v[148:151], v[168:171], v[60:63]
	v_mfma_f32_16x16x32_bf16 v[56:59], v[160:163], v[168:171], v[56:59]
	v_mfma_f32_16x16x32_bf16 v[52:55], v[148:151], v[178:181], v[52:55]
	v_mfma_f32_16x16x32_bf16 v[48:51], v[160:163], v[178:181], v[48:51]
	v_mfma_f32_16x16x32_bf16 v[44:47], v[148:151], v[186:189], v[44:47]
	v_mfma_f32_16x16x32_bf16 v[40:43], v[160:163], v[186:189], v[40:43]
	v_mfma_f32_16x16x32_bf16 v[36:39], v[148:151], v[194:197], v[36:39]
	v_mfma_f32_16x16x32_bf16 v[32:35], v[160:163], v[194:197], v[32:35]
	v_mfma_f32_16x16x32_bf16 v[60:63], v[152:155], v[172:175], v[60:63]
	v_mfma_f32_16x16x32_bf16 v[56:59], v[164:167], v[172:175], v[56:59]
	v_mfma_f32_16x16x32_bf16 v[52:55], v[152:155], v[182:185], v[52:55]
	v_mfma_f32_16x16x32_bf16 v[48:51], v[164:167], v[182:185], v[48:51]
	v_mfma_f32_16x16x32_bf16 v[44:47], v[152:155], v[190:193], v[44:47]
	v_mfma_f32_16x16x32_bf16 v[40:43], v[164:167], v[190:193], v[40:43]
	v_mfma_f32_16x16x32_bf16 v[36:39], v[152:155], v[198:201], v[36:39]
	v_mfma_f32_16x16x32_bf16 v[32:35], v[164:167], v[198:201], v[32:35]
	s_setprio 0
	s_setprio 1
	v_mfma_f32_16x16x32_bf16 v[28:31], v[202:205], v[168:171], v[28:31]
	v_mfma_f32_16x16x32_bf16 v[24:27], v[210:213], v[168:171], v[24:27]
	v_mfma_f32_16x16x32_bf16 v[20:23], v[202:205], v[178:181], v[20:23]
	v_mfma_f32_16x16x32_bf16 v[16:19], v[210:213], v[178:181], v[16:19]
	v_mfma_f32_16x16x32_bf16 v[12:15], v[202:205], v[186:189], v[12:15]
	v_mfma_f32_16x16x32_bf16 v[8:11], v[210:213], v[186:189], v[8:11]
	v_mfma_f32_16x16x32_bf16 v[4:7], v[202:205], v[194:197], v[4:7]
	v_mfma_f32_16x16x32_bf16 v[0:3], v[210:213], v[194:197], v[0:3]
	v_mfma_f32_16x16x32_bf16 v[28:31], v[206:209], v[172:175], v[28:31]
	v_mfma_f32_16x16x32_bf16 v[24:27], v[214:217], v[172:175], v[24:27]
	v_mfma_f32_16x16x32_bf16 v[20:23], v[206:209], v[182:185], v[20:23]
	v_mfma_f32_16x16x32_bf16 v[16:19], v[214:217], v[182:185], v[16:19]
	v_mfma_f32_16x16x32_bf16 v[12:15], v[206:209], v[190:193], v[12:15]
	v_mfma_f32_16x16x32_bf16 v[8:11], v[214:217], v[190:193], v[8:11]
	v_mfma_f32_16x16x32_bf16 v[4:7], v[206:209], v[198:201], v[4:7]
	v_mfma_f32_16x16x32_bf16 v[0:3], v[214:217], v[198:201], v[0:3]
	s_setprio 0
	s_barrier
	ds_read_b128 v[160:163], v141 offset:0
	ds_read_b128 v[164:167], v141 offset:1024
	ds_read_b128 v[168:171], v141 offset:2048
	ds_read_b128 v[172:175], v141 offset:3072
	s_add_u32 s40, s29, s38
	v_add_u32_e32 v150, 0x4000, v134
	s_addc_u32 s41, s30, s39
	v_readfirstlane_b32 s51, v150
	s_mov_b32 m0, s51
	v_add_u32_e32 v151, 0x6000, v134
	ds_read_b128 v[154:157], v140 offset:0
	ds_read_b128 v[178:181], v140 offset:1024
	ds_read_b128 v[182:185], v140 offset:2048
	ds_read_b128 v[186:189], v140 offset:3072
	ds_read_b128 v[190:193], v140 offset:4096
	ds_read_b128 v[194:197], v140 offset:5120
	ds_read_b128 v[198:201], v140 offset:6144
	ds_read_b128 v[202:205], v140 offset:7168
	global_load_lds_dwordx4 v128, s[40:41]
	s_add_u32 m0, m0, 0x2000
	s_nop 0
	global_load_lds_dwordx4 v130, s[40:41]
	ds_read_b128 v[206:209], v139 offset:0
	ds_read_b128 v[210:213], v139 offset:1024
	ds_read_b128 v[214:217], v139 offset:2048
	ds_read_b128 v[218:221], v139 offset:3072
	s_waitcnt vmcnt(8)
	s_waitcnt lgkmcnt(0)
	s_barrier
	s_waitcnt lgkmcnt(0)
	s_waitcnt lgkmcnt(0)
	s_setprio 1
	v_mfma_f32_16x16x32_bf16 v[124:127], v[160:163], v[154:157], v[124:127]
	v_mfma_f32_16x16x32_bf16 v[120:123], v[168:171], v[154:157], v[120:123]
	v_mfma_f32_16x16x32_bf16 v[116:119], v[160:163], v[182:185], v[116:119]
	v_mfma_f32_16x16x32_bf16 v[112:115], v[168:171], v[182:185], v[112:115]
	v_mfma_f32_16x16x32_bf16 v[108:111], v[160:163], v[190:193], v[108:111]
	v_mfma_f32_16x16x32_bf16 v[104:107], v[168:171], v[190:193], v[104:107]
	v_mfma_f32_16x16x32_bf16 v[100:103], v[160:163], v[198:201], v[100:103]
	v_mfma_f32_16x16x32_bf16 v[96:99], v[168:171], v[198:201], v[96:99]
	v_mfma_f32_16x16x32_bf16 v[124:127], v[164:167], v[178:181], v[124:127]
	v_mfma_f32_16x16x32_bf16 v[120:123], v[172:175], v[178:181], v[120:123]
	v_mfma_f32_16x16x32_bf16 v[116:119], v[164:167], v[186:189], v[116:119]
	v_mfma_f32_16x16x32_bf16 v[112:115], v[172:175], v[186:189], v[112:115]
	v_mfma_f32_16x16x32_bf16 v[108:111], v[164:167], v[194:197], v[108:111]
	v_mfma_f32_16x16x32_bf16 v[104:107], v[172:175], v[194:197], v[104:107]
	v_mfma_f32_16x16x32_bf16 v[100:103], v[164:167], v[202:205], v[100:103]
	v_mfma_f32_16x16x32_bf16 v[96:99], v[172:175], v[202:205], v[96:99]
	s_setprio 0
	s_waitcnt lgkmcnt(0)
	s_setprio 1
	v_mfma_f32_16x16x32_bf16 v[92:95], v[206:209], v[154:157], v[92:95]
	v_mfma_f32_16x16x32_bf16 v[88:91], v[214:217], v[154:157], v[88:91]
	v_mfma_f32_16x16x32_bf16 v[84:87], v[206:209], v[182:185], v[84:87]
	v_mfma_f32_16x16x32_bf16 v[80:83], v[214:217], v[182:185], v[80:83]
	v_mfma_f32_16x16x32_bf16 v[76:79], v[206:209], v[190:193], v[76:79]
	v_mfma_f32_16x16x32_bf16 v[72:75], v[214:217], v[190:193], v[72:75]
	v_mfma_f32_16x16x32_bf16 v[68:71], v[206:209], v[198:201], v[68:71]
	v_mfma_f32_16x16x32_bf16 v[64:67], v[214:217], v[198:201], v[64:67]
	v_mfma_f32_16x16x32_bf16 v[92:95], v[210:213], v[178:181], v[92:95]
	v_mfma_f32_16x16x32_bf16 v[88:91], v[218:221], v[178:181], v[88:91]
	v_mfma_f32_16x16x32_bf16 v[84:87], v[210:213], v[186:189], v[84:87]
	v_mfma_f32_16x16x32_bf16 v[80:83], v[218:221], v[186:189], v[80:83]
	v_mfma_f32_16x16x32_bf16 v[76:79], v[210:213], v[194:197], v[76:79]
	v_mfma_f32_16x16x32_bf16 v[72:75], v[218:221], v[194:197], v[72:75]
	v_mfma_f32_16x16x32_bf16 v[68:71], v[210:213], v[202:205], v[68:71]
	v_mfma_f32_16x16x32_bf16 v[64:67], v[218:221], v[202:205], v[64:67]
	s_setprio 0
	s_barrier
	s_add_u32 s40, s35, 0x180
	v_add_u32_e32 v152, 0x18000, v134
	s_addc_u32 s41, s42, 0
	v_readfirstlane_b32 s35, v152
	v_add_u32_e32 v153, 0x1a000, v134
	s_mov_b32 m0, s35
	global_load_lds_dwordx4 v176, s[40:41]
	s_add_u32 m0, m0, 0x2000
	s_nop 0
	global_load_lds_dwordx4 v132, s[40:41]
	s_add_u32 s40, s43, 0x180
	v_add_u32_e32 v154, 0x8000, v134
	s_addc_u32 s41, s45, 0
	v_readfirstlane_b32 s35, v154
	v_add_u32_e32 v155, 0xa000, v134
	s_mov_b32 m0, s35
	ds_read_b128 v[178:181], v138 offset:0
	ds_read_b128 v[182:185], v138 offset:1024
	ds_read_b128 v[186:189], v138 offset:2048
	ds_read_b128 v[190:193], v138 offset:3072
	ds_read_b128 v[194:197], v138 offset:4096
	ds_read_b128 v[198:201], v138 offset:5120
	ds_read_b128 v[202:205], v138 offset:6144
	ds_read_b128 v[222:225], v138 offset:7168
	global_load_lds_dwordx4 v128, s[40:41]
	s_add_u32 m0, m0, 0x2000
	s_nop 0
	global_load_lds_dwordx4 v130, s[40:41]
	s_add_u32 s40, s48, 0x180
	v_add_u32_e32 v156, 0x1c000, v134
	s_addc_u32 s41, s49, 0
	v_readfirstlane_b32 s35, v156
	v_add_u32_e32 v157, 0x1e000, v134
	s_mov_b32 m0, s35
	global_load_lds_dwordx4 v176, s[40:41]
	s_add_u32 m0, m0, 0x2000
	s_nop 0
	global_load_lds_dwordx4 v132, s[40:41]
	s_waitcnt vmcnt(8)
	s_waitcnt lgkmcnt(0)
	s_barrier
	s_waitcnt lgkmcnt(0)
	s_setprio 1
	v_mfma_f32_16x16x32_bf16 v[60:63], v[160:163], v[178:181], v[60:63]
	v_mfma_f32_16x16x32_bf16 v[56:59], v[168:171], v[178:181], v[56:59]
	v_mfma_f32_16x16x32_bf16 v[52:55], v[160:163], v[186:189], v[52:55]
	v_mfma_f32_16x16x32_bf16 v[48:51], v[168:171], v[186:189], v[48:51]
	v_mfma_f32_16x16x32_bf16 v[44:47], v[160:163], v[194:197], v[44:47]
	v_mfma_f32_16x16x32_bf16 v[40:43], v[168:171], v[194:197], v[40:43]
	v_mfma_f32_16x16x32_bf16 v[36:39], v[160:163], v[202:205], v[36:39]
	v_mfma_f32_16x16x32_bf16 v[32:35], v[168:171], v[202:205], v[32:35]
	v_mfma_f32_16x16x32_bf16 v[60:63], v[164:167], v[182:185], v[60:63]
	v_mfma_f32_16x16x32_bf16 v[56:59], v[172:175], v[182:185], v[56:59]
	v_mfma_f32_16x16x32_bf16 v[52:55], v[164:167], v[190:193], v[52:55]
	v_mfma_f32_16x16x32_bf16 v[48:51], v[172:175], v[190:193], v[48:51]
	v_mfma_f32_16x16x32_bf16 v[44:47], v[164:167], v[198:201], v[44:47]
	v_mfma_f32_16x16x32_bf16 v[40:43], v[172:175], v[198:201], v[40:43]
	v_mfma_f32_16x16x32_bf16 v[36:39], v[164:167], v[222:225], v[36:39]
	v_mfma_f32_16x16x32_bf16 v[32:35], v[172:175], v[222:225], v[32:35]
	s_setprio 0
	s_setprio 1
	v_mfma_f32_16x16x32_bf16 v[28:31], v[206:209], v[178:181], v[28:31]
	v_mfma_f32_16x16x32_bf16 v[24:27], v[214:217], v[178:181], v[24:27]
	v_mfma_f32_16x16x32_bf16 v[20:23], v[206:209], v[186:189], v[20:23]
	v_mfma_f32_16x16x32_bf16 v[16:19], v[214:217], v[186:189], v[16:19]
	v_mfma_f32_16x16x32_bf16 v[12:15], v[206:209], v[194:197], v[12:15]
	v_mfma_f32_16x16x32_bf16 v[8:11], v[214:217], v[194:197], v[8:11]
	v_mfma_f32_16x16x32_bf16 v[4:7], v[206:209], v[202:205], v[4:7]
	v_mfma_f32_16x16x32_bf16 v[0:3], v[214:217], v[202:205], v[0:3]
	v_mfma_f32_16x16x32_bf16 v[28:31], v[210:213], v[182:185], v[28:31]
	v_mfma_f32_16x16x32_bf16 v[24:27], v[218:221], v[182:185], v[24:27]
	v_mfma_f32_16x16x32_bf16 v[20:23], v[210:213], v[190:193], v[20:23]
	v_mfma_f32_16x16x32_bf16 v[16:19], v[218:221], v[190:193], v[16:19]
	v_mfma_f32_16x16x32_bf16 v[12:15], v[210:213], v[198:201], v[12:15]
	v_mfma_f32_16x16x32_bf16 v[8:11], v[218:221], v[198:201], v[8:11]
	v_mfma_f32_16x16x32_bf16 v[4:7], v[210:213], v[222:225], v[4:7]
	v_mfma_f32_16x16x32_bf16 v[0:3], v[218:221], v[222:225], v[0:3]
	s_setprio 0
	s_add_i32 s31, s31, 2
	s_add_u32 s38, s38, 0x100
	s_addc_u32 s39, s39, 0
	s_cmp_gt_u32 s31, 11
	s_barrier
	s_cbranch_scc0 .LBB0_141
	v_add_u32_e32 v158, 0xc000, v134
	v_add_u32_e32 v159, 0xe000, v134
	v_add_u32_e32 v146, 0x10000, v134
	v_add_u32_e32 v147, 0x12000, v134
	v_add_u32_e32 v148, 0x14000, v134
	v_add_u32_e32 v149, 0x16000, v134
	v_add_u32_e32 v150, 0x4000, v134
	v_add_u32_e32 v151, 0x6000, v134
	v_add_u32_e32 v152, 0x18000, v134
	v_add_u32_e32 v153, 0x1a000, v134
	v_add_u32_e32 v154, 0x8000, v134
	v_add_u32_e32 v155, 0xa000, v134
	v_add_u32_e32 v156, 0x1c000, v134
	v_add_u32_e32 v157, 0x1e000, v134
	s_add_u32 s2, s1, 0x780
	s_addc_u32 s3, s26, 0
	v_readfirstlane_b32 s1, v158
	v_lshl_add_u64 v[132:133], s[2:3], 0, v[128:129]
	s_mov_b32 m0, s1
	v_readfirstlane_b32 s1, v159
	ds_read_b128 v[160:163], v145 offset:0
	ds_read_b128 v[164:167], v145 offset:1024
	ds_read_b128 v[168:171], v145 offset:2048
	ds_read_b128 v[172:175], v145 offset:3072
	ds_read_b128 v[178:181], v144 offset:0
	ds_read_b128 v[182:185], v144 offset:1024
	ds_read_b128 v[190:193], v144 offset:2048
	ds_read_b128 v[194:197], v144 offset:3072
	ds_read_b128 v[198:201], v144 offset:4096
	ds_read_b128 v[202:205], v144 offset:5120
	ds_read_b128 v[206:209], v144 offset:6144
	ds_read_b128 v[210:213], v144 offset:7168
	global_load_lds_dwordx4 v[132:133], off
	v_lshl_add_u64 v[132:133], s[2:3], 0, v[130:131]
	s_mov_b32 m0, s1
	s_nop 0
	global_load_lds_dwordx4 v[132:133], off
	s_waitcnt vmcnt(10)
	s_barrier
	s_waitcnt lgkmcnt(0)
	s_waitcnt lgkmcnt(0)
	s_setprio 1
	v_mfma_f32_16x16x32_bf16 v[124:127], v[160:163], v[178:181], v[124:127]
	v_mfma_f32_16x16x32_bf16 v[116:119], v[160:163], v[190:193], v[116:119]
	v_mfma_f32_16x16x32_bf16 v[108:111], v[160:163], v[198:201], v[108:111]
	v_mfma_f32_16x16x32_bf16 v[100:103], v[160:163], v[206:209], v[100:103]
	v_mfma_f32_16x16x32_bf16 v[124:127], v[164:167], v[182:185], v[124:127]
	v_mfma_f32_16x16x32_bf16 v[120:123], v[168:171], v[178:181], v[120:123]
	v_mfma_f32_16x16x32_bf16 v[116:119], v[164:167], v[194:197], v[116:119]
	v_mfma_f32_16x16x32_bf16 v[112:115], v[168:171], v[190:193], v[112:115]
	v_mfma_f32_16x16x32_bf16 v[108:111], v[164:167], v[202:205], v[108:111]
	v_mfma_f32_16x16x32_bf16 v[104:107], v[168:171], v[198:201], v[104:107]
	v_mfma_f32_16x16x32_bf16 v[100:103], v[164:167], v[210:213], v[100:103]
	v_mfma_f32_16x16x32_bf16 v[96:99], v[168:171], v[206:209], v[96:99]
	v_mfma_f32_16x16x32_bf16 v[214:217], v[172:175], v[182:185], v[120:123]
	v_mfma_f32_16x16x32_bf16 v[218:221], v[172:175], v[194:197], v[112:115]
	v_mfma_f32_16x16x32_bf16 v[222:225], v[172:175], v[202:205], v[104:107]
	v_mfma_f32_16x16x32_bf16 v[226:229], v[172:175], v[210:213], v[96:99]
	s_setprio 0
	s_barrier
	ds_read_b128 v[96:99], v143 offset:0
	ds_read_b128 v[104:107], v143 offset:1024
	ds_read_b128 v[112:115], v143 offset:2048
	ds_read_b128 v[120:123], v143 offset:3072
	s_waitcnt vmcnt(8)
	s_barrier
	s_waitcnt lgkmcnt(0)
	s_setprio 1
	v_mfma_f32_16x16x32_bf16 v[92:95], v[96:99], v[178:181], v[92:95]
	v_mfma_f32_16x16x32_bf16 v[88:91], v[112:115], v[178:181], v[88:91]
	v_mfma_f32_16x16x32_bf16 v[84:87], v[96:99], v[190:193], v[84:87]
	v_mfma_f32_16x16x32_bf16 v[80:83], v[112:115], v[190:193], v[80:83]
	v_mfma_f32_16x16x32_bf16 v[76:79], v[96:99], v[198:201], v[76:79]
	v_mfma_f32_16x16x32_bf16 v[72:75], v[112:115], v[198:201], v[72:75]
	v_mfma_f32_16x16x32_bf16 v[68:71], v[96:99], v[206:209], v[68:71]
	v_mfma_f32_16x16x32_bf16 v[64:67], v[112:115], v[206:209], v[64:67]
	v_mfma_f32_16x16x32_bf16 v[92:95], v[104:107], v[182:185], v[92:95]
	v_mfma_f32_16x16x32_bf16 v[88:91], v[120:123], v[182:185], v[88:91]
	v_mfma_f32_16x16x32_bf16 v[84:87], v[104:107], v[194:197], v[84:87]
	v_mfma_f32_16x16x32_bf16 v[80:83], v[120:123], v[194:197], v[80:83]
	v_mfma_f32_16x16x32_bf16 v[76:79], v[104:107], v[202:205], v[76:79]
	v_mfma_f32_16x16x32_bf16 v[72:75], v[120:123], v[202:205], v[72:75]
	v_mfma_f32_16x16x32_bf16 v[68:71], v[104:107], v[210:213], v[68:71]
	v_mfma_f32_16x16x32_bf16 v[64:67], v[120:123], v[210:213], v[64:67]
	s_setprio 0
	s_barrier
	ds_read_b128 v[178:181], v142 offset:0
	ds_read_b128 v[182:185], v142 offset:1024
	ds_read_b128 v[190:193], v142 offset:2048
	ds_read_b128 v[194:197], v142 offset:3072
	ds_read_b128 v[198:201], v142 offset:4096
	ds_read_b128 v[202:205], v142 offset:5120
	ds_read_b128 v[206:209], v142 offset:6144
	ds_read_b128 v[142:145], v142 offset:7168
	s_waitcnt vmcnt(4)
	s_barrier
	s_waitcnt lgkmcnt(0)
	s_setprio 1
	v_mfma_f32_16x16x32_bf16 v[60:63], v[160:163], v[178:181], v[60:63]
	v_mfma_f32_16x16x32_bf16 v[210:213], v[164:167], v[182:185], v[60:63]
	v_mfma_f32_16x16x32_bf16 v[56:59], v[168:171], v[178:181], v[56:59]
	v_mfma_f32_16x16x32_bf16 v[52:55], v[160:163], v[190:193], v[52:55]
	v_mfma_f32_16x16x32_bf16 v[48:51], v[168:171], v[190:193], v[48:51]
	v_mfma_f32_16x16x32_bf16 v[44:47], v[160:163], v[198:201], v[44:47]
	v_mfma_f32_16x16x32_bf16 v[40:43], v[168:171], v[198:201], v[40:43]
	v_mfma_f32_16x16x32_bf16 v[36:39], v[160:163], v[206:209], v[36:39]
	v_mfma_f32_16x16x32_bf16 v[32:35], v[168:171], v[206:209], v[32:35]
	v_mfma_f32_16x16x32_bf16 v[238:241], v[172:175], v[182:185], v[56:59]
	v_mfma_f32_16x16x32_bf16 v[242:245], v[164:167], v[194:197], v[52:55]
	v_mfma_f32_16x16x32_bf16 v[246:249], v[172:175], v[194:197], v[48:51]
	v_mfma_f32_16x16x32_bf16 v[232:235], v[164:167], v[202:205], v[44:47]
	v_mfma_f32_16x16x32_bf16 v[186:189], v[172:175], v[202:205], v[40:43]
	v_mfma_f32_16x16x32_bf16 v[158:161], v[164:167], v[142:145], v[36:39]
	v_mfma_f32_16x16x32_bf16 v[162:165], v[172:175], v[142:145], v[32:35]
	s_setprio 0
	s_setprio 1
	v_mfma_f32_16x16x32_bf16 v[28:31], v[96:99], v[178:181], v[28:31]
	v_mfma_f32_16x16x32_bf16 v[20:23], v[96:99], v[190:193], v[20:23]
	v_mfma_f32_16x16x32_bf16 v[12:15], v[96:99], v[198:201], v[12:15]
	v_mfma_f32_16x16x32_bf16 v[4:7], v[96:99], v[206:209], v[4:7]
	v_mfma_f32_16x16x32_bf16 v[28:31], v[104:107], v[182:185], v[28:31]
	v_mfma_f32_16x16x32_bf16 v[24:27], v[112:115], v[178:181], v[24:27]
	v_mfma_f32_16x16x32_bf16 v[20:23], v[104:107], v[194:197], v[20:23]
	v_mfma_f32_16x16x32_bf16 v[16:19], v[112:115], v[190:193], v[16:19]
	v_mfma_f32_16x16x32_bf16 v[12:15], v[104:107], v[202:205], v[12:15]
	v_mfma_f32_16x16x32_bf16 v[8:11], v[112:115], v[198:201], v[8:11]
	v_mfma_f32_16x16x32_bf16 v[4:7], v[104:107], v[142:145], v[4:7]
	v_mfma_f32_16x16x32_bf16 v[0:3], v[112:115], v[206:209], v[0:3]
	v_mfma_f32_16x16x32_bf16 v[166:169], v[120:123], v[182:185], v[24:27]
	v_mfma_f32_16x16x32_bf16 v[170:173], v[120:123], v[194:197], v[16:19]
	v_mfma_f32_16x16x32_bf16 v[178:181], v[120:123], v[202:205], v[8:11]
	v_mfma_f32_16x16x32_bf16 v[142:145], v[120:123], v[142:145], v[0:3]
	s_setprio 0
	s_barrier
	ds_read_b128 v[0:3], v141 offset:0
	ds_read_b128 v[8:11], v141 offset:1024
	ds_read_b128 v[16:19], v141 offset:2048
	ds_read_b128 v[24:27], v141 offset:3072
	ds_read_b128 v[32:35], v140 offset:0
	ds_read_b128 v[36:39], v140 offset:1024
	ds_read_b128 v[40:43], v140 offset:2048
	ds_read_b128 v[44:47], v140 offset:3072
	ds_read_b128 v[182:185], v140 offset:4096
	ds_read_b128 v[190:193], v140 offset:5120
	ds_read_b128 v[194:197], v140 offset:6144
	ds_read_b128 v[198:201], v140 offset:7168
	s_waitcnt vmcnt(2)
	s_barrier
	s_waitcnt lgkmcnt(0)
	s_waitcnt lgkmcnt(0)
	s_setprio 1
	v_mfma_f32_16x16x32_bf16 v[48:51], v[0:3], v[32:35], v[124:127]
	v_mfma_f32_16x16x32_bf16 v[120:123], v[8:11], v[36:39], v[48:51]
	v_mfma_f32_16x16x32_bf16 v[48:51], v[16:19], v[32:35], v[214:217]
	v_mfma_f32_16x16x32_bf16 v[124:127], v[24:27], v[36:39], v[48:51]
	v_mfma_f32_16x16x32_bf16 v[48:51], v[0:3], v[40:43], v[116:119]
	v_mfma_f32_16x16x32_bf16 v[112:115], v[8:11], v[44:47], v[48:51]
	v_mfma_f32_16x16x32_bf16 v[48:51], v[16:19], v[40:43], v[218:221]
	v_mfma_f32_16x16x32_bf16 v[116:119], v[24:27], v[44:47], v[48:51]
	v_mfma_f32_16x16x32_bf16 v[48:51], v[0:3], v[182:185], v[108:111]
	v_mfma_f32_16x16x32_bf16 v[104:107], v[8:11], v[190:193], v[48:51]
	v_mfma_f32_16x16x32_bf16 v[48:51], v[16:19], v[182:185], v[222:225]
	v_mfma_f32_16x16x32_bf16 v[108:111], v[24:27], v[190:193], v[48:51]
	v_mfma_f32_16x16x32_bf16 v[48:51], v[0:3], v[194:197], v[100:103]
	v_mfma_f32_16x16x32_bf16 v[96:99], v[8:11], v[198:201], v[48:51]
	v_mfma_f32_16x16x32_bf16 v[48:51], v[16:19], v[194:197], v[226:229]
	v_mfma_f32_16x16x32_bf16 v[100:103], v[24:27], v[198:201], v[48:51]
	s_setprio 0
	s_barrier
	ds_read_b128 v[202:205], v139 offset:0
	ds_read_b128 v[206:209], v139 offset:1024
	ds_read_b128 v[214:217], v139 offset:2048
	ds_read_b128 v[218:221], v139 offset:3072
	s_waitcnt vmcnt(0)
	s_barrier
	s_waitcnt lgkmcnt(0)
	s_setprio 1
	v_mfma_f32_16x16x32_bf16 v[48:51], v[202:205], v[32:35], v[92:95]
	v_mfma_f32_16x16x32_bf16 v[32:35], v[214:217], v[32:35], v[88:91]
	v_mfma_f32_16x16x32_bf16 v[60:63], v[218:221], v[36:39], v[32:35]
	v_mfma_f32_16x16x32_bf16 v[32:35], v[202:205], v[40:43], v[84:87]
	v_mfma_f32_16x16x32_bf16 v[56:59], v[206:209], v[44:47], v[32:35]
	v_mfma_f32_16x16x32_bf16 v[32:35], v[214:217], v[40:43], v[80:83]
	v_mfma_f32_16x16x32_bf16 v[52:55], v[218:221], v[44:47], v[32:35]
	v_mfma_f32_16x16x32_bf16 v[32:35], v[202:205], v[182:185], v[76:79]
	v_mfma_f32_16x16x32_bf16 v[92:95], v[206:209], v[36:39], v[48:51]
	v_mfma_f32_16x16x32_bf16 v[48:51], v[206:209], v[190:193], v[32:35]
	v_mfma_f32_16x16x32_bf16 v[32:35], v[214:217], v[182:185], v[72:75]
	v_mfma_f32_16x16x32_bf16 v[44:47], v[218:221], v[190:193], v[32:35]
	v_mfma_f32_16x16x32_bf16 v[32:35], v[202:205], v[194:197], v[68:71]
	v_mfma_f32_16x16x32_bf16 v[36:39], v[214:217], v[194:197], v[64:67]
	v_mfma_f32_16x16x32_bf16 v[40:43], v[206:209], v[198:201], v[32:35]
	v_mfma_f32_16x16x32_bf16 v[36:39], v[218:221], v[198:201], v[36:39]
	s_setprio 0
	s_barrier
	ds_read_b128 v[182:185], v138 offset:0
	ds_read_b128 v[190:193], v138 offset:1024
	ds_read_b128 v[194:197], v138 offset:2048
	ds_read_b128 v[198:201], v138 offset:3072
	ds_read_b128 v[222:225], v138 offset:4096
	ds_read_b128 v[226:229], v138 offset:5120
	ds_read_b128 v[32:35], v138 offset:6144
	ds_read_b128 v[138:141], v138 offset:7168
	s_barrier
	s_waitcnt lgkmcnt(0)
	s_setprio 1
	v_mfma_f32_16x16x32_bf16 v[64:67], v[0:3], v[182:185], v[210:213]
	v_mfma_f32_16x16x32_bf16 v[88:91], v[8:11], v[190:193], v[64:67]
	v_mfma_f32_16x16x32_bf16 v[64:67], v[16:19], v[182:185], v[238:241]
	v_mfma_f32_16x16x32_bf16 v[210:213], v[24:27], v[190:193], v[64:67]
	v_mfma_f32_16x16x32_bf16 v[64:67], v[0:3], v[194:197], v[242:245]
	v_mfma_f32_16x16x32_bf16 v[80:83], v[8:11], v[198:201], v[64:67]
	v_mfma_f32_16x16x32_bf16 v[64:67], v[16:19], v[194:197], v[246:249]
	v_mfma_f32_16x16x32_bf16 v[84:87], v[24:27], v[198:201], v[64:67]
	v_mfma_f32_16x16x32_bf16 v[64:67], v[0:3], v[222:225], v[232:235]
	v_mfma_f32_16x16x32_bf16 v[72:75], v[8:11], v[226:229], v[64:67]
	v_mfma_f32_16x16x32_bf16 v[64:67], v[16:19], v[222:225], v[186:189]
	v_mfma_f32_16x16x32_bf16 v[0:3], v[0:3], v[32:35], v[158:161]
	v_mfma_f32_16x16x32_bf16 v[76:79], v[24:27], v[226:229], v[64:67]
	v_mfma_f32_16x16x32_bf16 v[64:67], v[8:11], v[138:141], v[0:3]
	v_mfma_f32_16x16x32_bf16 v[0:3], v[16:19], v[32:35], v[162:165]
	v_mfma_f32_16x16x32_bf16 v[68:71], v[24:27], v[138:141], v[0:3]
	s_setprio 0
	s_setprio 1
	v_mfma_f32_16x16x32_bf16 v[0:3], v[202:205], v[182:185], v[28:31]
	v_mfma_f32_16x16x32_bf16 v[24:27], v[206:209], v[190:193], v[0:3]
	v_mfma_f32_16x16x32_bf16 v[0:3], v[214:217], v[182:185], v[166:169]
	v_mfma_f32_16x16x32_bf16 v[28:31], v[218:221], v[190:193], v[0:3]
	v_mfma_f32_16x16x32_bf16 v[0:3], v[202:205], v[194:197], v[20:23]
	v_mfma_f32_16x16x32_bf16 v[16:19], v[206:209], v[198:201], v[0:3]
	v_mfma_f32_16x16x32_bf16 v[0:3], v[214:217], v[194:197], v[170:173]
	v_mfma_f32_16x16x32_bf16 v[20:23], v[218:221], v[198:201], v[0:3]
	v_mfma_f32_16x16x32_bf16 v[0:3], v[202:205], v[222:225], v[12:15]
	v_mfma_f32_16x16x32_bf16 v[8:11], v[206:209], v[226:229], v[0:3]
	v_mfma_f32_16x16x32_bf16 v[0:3], v[214:217], v[222:225], v[178:181]
	v_mfma_f32_16x16x32_bf16 v[12:15], v[218:221], v[226:229], v[0:3]
	v_mfma_f32_16x16x32_bf16 v[0:3], v[202:205], v[32:35], v[4:7]
	v_mfma_f32_16x16x32_bf16 v[4:7], v[214:217], v[32:35], v[142:145]
	v_mfma_f32_16x16x32_bf16 v[0:3], v[206:209], v[138:141], v[0:3]
	v_mfma_f32_16x16x32_bf16 v[4:7], v[218:221], v[138:141], v[4:7]
	s_setprio 0
	s_cmpk_lt_u32 s11, 0x100
	s_barrier
	s_cbranch_scc0 .LBB0_144
	s_barrier
